# baseline (speedup 1.0000x reference)
.LBB0_121:
	s_lshl_b32 s19, s8, 1
	s_lshl_b32 s20, s13, 1
	v_or_b32_e32 v4, s20, v30
	s_add_i32 s22, s19, 4
	s_add_i32 s23, s20, 4
	v_mov_b32_e32 v39, v5
	s_add_i32 s25, s20, 8
	v_lshlrev_b64 v[52:53], 13, v[4:5]
	v_or_b32_e32 v38, s22, v3
	v_or_b32_e32 v4, s23, v30
	v_mov_b32_e32 v37, v5
	v_or_b32_e32 v36, s19, v3
	s_add_i32 s27, s20, 12
	v_lshlrev_b64 v[38:39], 13, v[38:39]
	v_lshlrev_b64 v[54:55], 13, v[4:5]
	v_or_b32_e32 v4, s25, v30
	s_add_i32 s24, s19, 8
	s_add_i32 s26, s19, 12
	s_add_i32 s29, s20, 16
	v_lshlrev_b64 v[36:37], 13, v[36:37]
	v_lshl_add_u64 v[52:53], v[28:29], 0, v[52:53]
	v_lshl_add_u64 v[38:39], v[28:29], 0, v[38:39]
	v_lshlrev_b64 v[56:57], 13, v[4:5]
	v_or_b32_e32 v4, s27, v30
	v_mov_b32_e32 v41, v5
	v_mov_b32_e32 v43, v5
	s_add_i32 s31, s20, 20
	v_or_b32_e32 v40, s24, v3
	v_or_b32_e32 v42, s26, v3
	v_lshl_add_u64 v[36:37], v[28:29], 0, v[36:37]
	v_lshl_add_u64 v[54:55], v[28:29], 0, v[54:55]
	global_load_dword v25, v[52:53], off
	global_load_dword v27, v[36:37], off
	global_load_dword v35, v[54:55], off
	global_load_dword v68, v[38:39], off
	v_lshlrev_b64 v[38:39], 13, v[4:5]
	v_or_b32_e32 v4, s29, v30
	s_add_i32 s28, s19, 16
	s_add_i32 s30, s19, 20
	s_add_i32 s34, s20, 24
	v_lshlrev_b64 v[40:41], 13, v[40:41]
	v_lshlrev_b64 v[42:43], 13, v[42:43]
	v_lshl_add_u64 v[36:37], v[28:29], 0, v[56:57]
	v_lshl_add_u64 v[38:39], v[28:29], 0, v[38:39]
	v_lshlrev_b64 v[52:53], 13, v[4:5]
	v_or_b32_e32 v4, s31, v30
	v_mov_b32_e32 v45, v5
	v_mov_b32_e32 v47, v5
	s_add_i32 s33, s19, 24
	s_add_i32 s35, s19, 28
	s_add_i32 s36, s20, 28
	v_or_b32_e32 v44, s28, v3
	v_or_b32_e32 v46, s30, v3
	v_lshl_add_u64 v[40:41], v[28:29], 0, v[40:41]
	v_lshl_add_u64 v[42:43], v[28:29], 0, v[42:43]
	global_load_dword v69, v[36:37], off
	global_load_dword v70, v[40:41], off
	global_load_dword v71, v[38:39], off
	global_load_dword v72, v[42:43], off
	v_lshlrev_b64 v[38:39], 13, v[4:5]
	v_or_b32_e32 v4, s34, v30
	v_mov_b32_e32 v49, v5
	v_mov_b32_e32 v51, v5
	v_or_b32_e32 v48, s33, v3
	v_or_b32_e32 v50, s35, v3
	v_lshlrev_b64 v[44:45], 13, v[44:45]
	v_lshlrev_b64 v[46:47], 13, v[46:47]
	v_lshl_add_u64 v[36:37], v[28:29], 0, v[52:53]
	v_lshl_add_u64 v[38:39], v[28:29], 0, v[38:39]
	v_lshlrev_b64 v[40:41], 13, v[4:5]
	v_or_b32_e32 v4, s36, v30
	v_lshlrev_b64 v[48:49], 13, v[48:49]
	v_lshlrev_b64 v[50:51], 13, v[50:51]
	v_lshl_add_u64 v[44:45], v[28:29], 0, v[44:45]
	v_lshl_add_u64 v[46:47], v[28:29], 0, v[46:47]
	global_load_dword v73, v[36:37], off
	global_load_dword v74, v[44:45], off
	global_load_dword v75, v[38:39], off
	global_load_dword v76, v[46:47], off
	v_lshl_add_u64 v[36:37], v[28:29], 0, v[40:41]
	v_lshlrev_b64 v[38:39], 13, v[4:5]
	v_lshl_add_u64 v[48:49], v[28:29], 0, v[48:49]
	v_lshl_add_u64 v[50:51], v[28:29], 0, v[50:51]
	v_lshl_add_u64 v[38:39], v[28:29], 0, v[38:39]
	global_load_dword v4, v[36:37], off
	global_load_dword v77, v[48:49], off
	global_load_dword v78, v[38:39], off
	global_load_dword v79, v[50:51], off
	v_or_b32_e32 v38, s19, v1
	v_or_b32_e32 v36, s20, v2
	s_add_i32 s13, s13, 16
	s_add_i32 s8, s8, 16
	s_add_i32 s18, s18, -16
	v_mad_u64_u32 v[36:37], vcc, v36, s17, v[6:7]
	v_mad_u64_u32 v[38:39], vcc, v38, s17, v[6:7]
	v_or_b32_e32 v37, s22, v1
	v_or_b32_e32 v39, s23, v2
	v_or_b32_e32 v46, s24, v1
	v_or_b32_e32 v44, s25, v2
	v_or_b32_e32 v50, s26, v1
	v_or_b32_e32 v48, s27, v2
	v_or_b32_e32 v54, s28, v1
	v_or_b32_e32 v52, s29, v2
	v_or_b32_e32 v58, s30, v1
	v_or_b32_e32 v56, s31, v2
	v_or_b32_e32 v62, s33, v1
	v_or_b32_e32 v60, s34, v2
	v_or_b32_e32 v66, s35, v1
	v_or_b32_e32 v64, s36, v2
	s_cmp_lg_u32 s18, 0
	v_mad_u64_u32 v[40:41], vcc, v39, s17, v[6:7]
	v_mad_u64_u32 v[42:43], vcc, v37, s17, v[6:7]
	v_mad_u64_u32 v[44:45], vcc, v44, s17, v[6:7]
	v_mad_u64_u32 v[46:47], vcc, v46, s17, v[6:7]
	v_mad_u64_u32 v[48:49], vcc, v48, s17, v[6:7]
	v_mad_u64_u32 v[50:51], vcc, v50, s17, v[6:7]
	v_mad_u64_u32 v[52:53], vcc, v52, s17, v[6:7]
	v_mad_u64_u32 v[54:55], vcc, v54, s17, v[6:7]
	v_mad_u64_u32 v[56:57], vcc, v56, s17, v[6:7]
	v_mad_u64_u32 v[58:59], vcc, v58, s17, v[6:7]
	v_mad_u64_u32 v[60:61], vcc, v60, s17, v[6:7]
	v_mad_u64_u32 v[62:63], vcc, v62, s17, v[6:7]
	v_mad_u64_u32 v[64:65], vcc, v64, s17, v[6:7]
	v_mad_u64_u32 v[66:67], vcc, v66, s17, v[6:7]
	s_nop 3
	v_mov_b32_e32 v181, v5
	s_lshl_b32 s19, s8, 1
	s_lshl_b32 s20, s13, 1
	v_or_b32_e32 v180, s20, v30
	s_add_i32 s22, s19, 4
	s_add_i32 s23, s20, 4
	v_mov_b32_e32 v139, v181
	s_add_i32 s25, s20, 8
	v_lshlrev_b64 v[152:153], 13, v[180:181]
	v_or_b32_e32 v138, s22, v3
	v_or_b32_e32 v180, s23, v30
	v_mov_b32_e32 v137, v181
	v_or_b32_e32 v136, s19, v3
	s_add_i32 s27, s20, 12
	v_lshlrev_b64 v[138:139], 13, v[138:139]
	v_lshlrev_b64 v[154:155], 13, v[180:181]
	v_or_b32_e32 v180, s25, v30
	s_add_i32 s24, s19, 8
	s_add_i32 s26, s19, 12
	s_add_i32 s29, s20, 16
	v_lshlrev_b64 v[136:137], 13, v[136:137]
	v_lshl_add_u64 v[152:153], v[28:29], 0, v[152:153]
	v_lshl_add_u64 v[138:139], v[28:29], 0, v[138:139]
	v_lshlrev_b64 v[156:157], 13, v[180:181]
	v_or_b32_e32 v180, s27, v30
	v_mov_b32_e32 v141, v181
	v_mov_b32_e32 v143, v181
	s_add_i32 s31, s20, 20
	v_or_b32_e32 v140, s24, v3
	v_or_b32_e32 v142, s26, v3
	v_lshl_add_u64 v[136:137], v[28:29], 0, v[136:137]
	v_lshl_add_u64 v[154:155], v[28:29], 0, v[154:155]
	global_load_dword v182, v[152:153], off
	global_load_dword v183, v[136:137], off
	global_load_dword v135, v[154:155], off
	global_load_dword v168, v[138:139], off
	v_lshlrev_b64 v[138:139], 13, v[180:181]
	v_or_b32_e32 v180, s29, v30
	s_add_i32 s28, s19, 16
	s_add_i32 s30, s19, 20
	s_add_i32 s34, s20, 24
	v_lshlrev_b64 v[140:141], 13, v[140:141]
	v_lshlrev_b64 v[142:143], 13, v[142:143]
	v_lshl_add_u64 v[136:137], v[28:29], 0, v[156:157]
	v_lshl_add_u64 v[138:139], v[28:29], 0, v[138:139]
	v_lshlrev_b64 v[152:153], 13, v[180:181]
	v_or_b32_e32 v180, s31, v30
	v_mov_b32_e32 v145, v181
	v_mov_b32_e32 v147, v181
	s_add_i32 s33, s19, 24
	s_add_i32 s35, s19, 28
	s_add_i32 s36, s20, 28
	v_or_b32_e32 v144, s28, v3
	v_or_b32_e32 v146, s30, v3
	v_lshl_add_u64 v[140:141], v[28:29], 0, v[140:141]
	v_lshl_add_u64 v[142:143], v[28:29], 0, v[142:143]
	global_load_dword v169, v[136:137], off
	global_load_dword v170, v[140:141], off
	global_load_dword v171, v[138:139], off
	global_load_dword v172, v[142:143], off
	v_lshlrev_b64 v[138:139], 13, v[180:181]
	v_or_b32_e32 v180, s34, v30
	v_mov_b32_e32 v149, v181
	v_mov_b32_e32 v151, v181
	v_or_b32_e32 v148, s33, v3
	v_or_b32_e32 v150, s35, v3
	v_lshlrev_b64 v[144:145], 13, v[144:145]
	v_lshlrev_b64 v[146:147], 13, v[146:147]
	v_lshl_add_u64 v[136:137], v[28:29], 0, v[152:153]
	v_lshl_add_u64 v[138:139], v[28:29], 0, v[138:139]
	v_lshlrev_b64 v[140:141], 13, v[180:181]
	v_or_b32_e32 v180, s36, v30
	v_lshlrev_b64 v[148:149], 13, v[148:149]
	v_lshlrev_b64 v[150:151], 13, v[150:151]
	v_lshl_add_u64 v[144:145], v[28:29], 0, v[144:145]
	v_lshl_add_u64 v[146:147], v[28:29], 0, v[146:147]
	global_load_dword v173, v[136:137], off
	global_load_dword v174, v[144:145], off
	global_load_dword v175, v[138:139], off
	global_load_dword v176, v[146:147], off
	v_lshl_add_u64 v[136:137], v[28:29], 0, v[140:141]
	v_lshlrev_b64 v[138:139], 13, v[180:181]
	v_lshl_add_u64 v[148:149], v[28:29], 0, v[148:149]
	v_lshl_add_u64 v[150:151], v[28:29], 0, v[150:151]
	v_lshl_add_u64 v[138:139], v[28:29], 0, v[138:139]
	global_load_dword v180, v[136:137], off
	global_load_dword v177, v[148:149], off
	global_load_dword v178, v[138:139], off
	global_load_dword v179, v[150:151], off
	s_waitcnt vmcnt(31)
	ds_write_b32 v36, v25
	s_waitcnt vmcnt(30)
	ds_write_b32 v38, v27
	s_waitcnt vmcnt(29)
	ds_write_b32 v40, v35
	s_waitcnt vmcnt(28)
	ds_write_b32 v42, v68
	s_waitcnt vmcnt(27)
	ds_write_b32 v44, v69
	s_waitcnt vmcnt(26)
	ds_write_b32 v46, v70
	s_waitcnt vmcnt(25)
	ds_write_b32 v48, v71
	s_waitcnt vmcnt(24)
	ds_write_b32 v50, v72
	s_waitcnt vmcnt(23)
	ds_write_b32 v52, v73
	s_waitcnt vmcnt(22)
	ds_write_b32 v54, v74
	s_waitcnt vmcnt(21)
	ds_write_b32 v56, v75
	s_waitcnt vmcnt(20)
	ds_write_b32 v58, v76
	s_waitcnt vmcnt(19)
	ds_write_b32 v60, v4
	s_waitcnt vmcnt(18)
	ds_write_b32 v62, v77
	s_waitcnt vmcnt(17)
	ds_write_b32 v64, v78
	s_waitcnt vmcnt(16)
	ds_write_b32 v66, v79
	v_or_b32_e32 v138, s19, v1
	v_or_b32_e32 v136, s20, v2
	s_add_i32 s13, s13, 16
	s_add_i32 s8, s8, 16
	s_add_i32 s18, s18, -16
	v_mad_u64_u32 v[136:137], vcc, v136, s17, v[6:7]
	v_mad_u64_u32 v[138:139], vcc, v138, s17, v[6:7]
	v_or_b32_e32 v137, s22, v1
	v_or_b32_e32 v139, s23, v2
	v_or_b32_e32 v146, s24, v1
	v_or_b32_e32 v144, s25, v2
	v_or_b32_e32 v150, s26, v1
	v_or_b32_e32 v148, s27, v2
	v_or_b32_e32 v154, s28, v1
	v_or_b32_e32 v152, s29, v2
	v_or_b32_e32 v158, s30, v1
	v_or_b32_e32 v156, s31, v2
	v_or_b32_e32 v162, s33, v1
	v_or_b32_e32 v160, s34, v2
	v_or_b32_e32 v166, s35, v1
	v_or_b32_e32 v164, s36, v2
	s_cmp_lg_u32 s18, 0
	v_mad_u64_u32 v[140:141], vcc, v139, s17, v[6:7]
	v_mad_u64_u32 v[142:143], vcc, v137, s17, v[6:7]
	v_mad_u64_u32 v[144:145], vcc, v144, s17, v[6:7]
	v_mad_u64_u32 v[146:147], vcc, v146, s17, v[6:7]
	v_mad_u64_u32 v[148:149], vcc, v148, s17, v[6:7]
	v_mad_u64_u32 v[150:151], vcc, v150, s17, v[6:7]
	v_mad_u64_u32 v[152:153], vcc, v152, s17, v[6:7]
	v_mad_u64_u32 v[154:155], vcc, v154, s17, v[6:7]
	v_mad_u64_u32 v[156:157], vcc, v156, s17, v[6:7]
	v_mad_u64_u32 v[158:159], vcc, v158, s17, v[6:7]
	v_mad_u64_u32 v[160:161], vcc, v160, s17, v[6:7]
	v_mad_u64_u32 v[162:163], vcc, v162, s17, v[6:7]
	v_mad_u64_u32 v[164:165], vcc, v164, s17, v[6:7]
	v_mad_u64_u32 v[166:167], vcc, v166, s17, v[6:7]
	s_waitcnt vmcnt(15)
	ds_write_b32 v136, v182
	s_waitcnt vmcnt(14)
	ds_write_b32 v138, v183
	s_waitcnt vmcnt(13)
	ds_write_b32 v140, v135
	s_waitcnt vmcnt(12)
	ds_write_b32 v142, v168
	s_waitcnt vmcnt(11)
	ds_write_b32 v144, v169
	s_waitcnt vmcnt(10)
	ds_write_b32 v146, v170
	s_waitcnt vmcnt(9)
	ds_write_b32 v148, v171
	s_waitcnt vmcnt(8)
	ds_write_b32 v150, v172
	s_waitcnt vmcnt(7)
	ds_write_b32 v152, v173
	s_waitcnt vmcnt(6)
	ds_write_b32 v154, v174
	s_waitcnt vmcnt(5)
	ds_write_b32 v156, v175
	s_waitcnt vmcnt(4)
	ds_write_b32 v158, v176
	s_waitcnt vmcnt(3)
	ds_write_b32 v160, v180
	s_waitcnt vmcnt(2)
	ds_write_b32 v162, v177
	s_waitcnt vmcnt(1)
	ds_write_b32 v164, v178
	s_waitcnt vmcnt(0)
	ds_write_b32 v166, v179
	s_waitcnt lgkmcnt(0)
	ds_read2_b32 v[40:41], v31 offset0:33 offset1:41
	ds_read2_b32 v[42:43], v31 offset1:8
	ds_read2_b32 v[44:45], v31 offset0:66 offset1:74
	ds_read2_b32 v[46:47], v31 offset0:99 offset1:107
	ds_read2_b32 v[48:49], v31 offset0:132 offset1:140
	ds_read2_b32 v[50:51], v31 offset0:165 offset1:173
	ds_read2_b32 v[52:53], v31 offset0:198 offset1:206
	ds_read2_b32 v[54:55], v31 offset0:231 offset1:239
	v_lshl_add_u64 v[28:29], s[4:5], 1, v[8:9]
	s_lshl_b32 s8, s3, 1
	v_lshl_add_u64 v[28:29], v[28:29], 0, s[8:9]
	v_mov_b32_e32 v27, v5
	v_or_b32_e32 v3, s2, v7
	v_lshl_add_u64 v[28:29], v[28:29], 0, v[26:27]
	v_lshlrev_b32_e32 v4, 14, v3
	s_waitcnt lgkmcnt(6)
	v_cvt_pk_bf16_f32 v36, v42, v40
	s_waitcnt lgkmcnt(4)
	v_cvt_pk_bf16_f32 v37, v44, v46
	s_waitcnt lgkmcnt(2)
	v_cvt_pk_bf16_f32 v38, v48, v50
	s_waitcnt lgkmcnt(0)
	v_cvt_pk_bf16_f32 v39, v52, v54
	v_lshl_add_u64 v[56:57], v[28:29], 0, v[4:5]
	global_store_dwordx4 v[56:57], v[36:39], off
	v_or_b32_e32 v3, s2, v32
	v_lshlrev_b32_e32 v4, 14, v3
	v_cvt_pk_bf16_f32 v36, v43, v41
	v_cvt_pk_bf16_f32 v37, v45, v47
	v_cvt_pk_bf16_f32 v38, v49, v51
	v_cvt_pk_bf16_f32 v39, v53, v55
	ds_read2_b32 v[42:43], v31 offset0:49 offset1:57
	ds_read2_b32 v[44:45], v31 offset0:16 offset1:24
	ds_read2_b32 v[46:47], v31 offset0:82 offset1:90
	ds_read2_b32 v[48:49], v31 offset0:115 offset1:123
	ds_read2_b32 v[50:51], v31 offset0:148 offset1:156
	ds_read2_b32 v[52:53], v31 offset0:181 offset1:189
	ds_read2_b32 v[54:55], v31 offset0:214 offset1:222
	ds_read2_b32 v[56:57], v31 offset0:247 offset1:255
	v_or_b32_e32 v3, s2, v33
	v_lshl_add_u64 v[40:41], v[28:29], 0, v[4:5]
	v_lshlrev_b32_e32 v4, 14, v3
	v_or_b32_e32 v3, s2, v34
	global_store_dwordx4 v[40:41], v[36:39], off
	v_lshl_add_u64 v[40:41], v[28:29], 0, v[4:5]
	v_lshlrev_b32_e32 v4, 14, v3
	s_waitcnt lgkmcnt(6)
	v_cvt_pk_bf16_f32 v36, v44, v42
	s_waitcnt lgkmcnt(4)
	v_cvt_pk_bf16_f32 v37, v46, v48
	s_waitcnt lgkmcnt(2)
	v_cvt_pk_bf16_f32 v38, v50, v52
	s_waitcnt lgkmcnt(0)
	v_cvt_pk_bf16_f32 v39, v54, v56
	global_store_dwordx4 v[40:41], v[36:39], off
	v_lshl_add_u64 v[28:29], v[28:29], 0, v[4:5]
	s_mov_b64 s[2:3], 0
	v_cvt_pk_bf16_f32 v36, v45, v43
	v_cvt_pk_bf16_f32 v37, v47, v49
	v_cvt_pk_bf16_f32 v38, v51, v53
	v_cvt_pk_bf16_f32 v39, v55, v57
	global_store_dwordx4 v[28:29], v[36:39], off
	s_waitcnt lgkmcnt(0)

.LBB0_125:
	s_lshl_b32 s18, s8, 1
	s_lshl_b32 s19, s12, 1
	v_or_b32_e32 v4, s19, v30
	s_add_i32 s20, s18, 4
	s_add_i32 s21, s19, 4
	v_mov_b32_e32 v39, v5
	s_add_i32 s23, s19, 8
	v_lshlrev_b64 v[52:53], 15, v[4:5]
	v_or_b32_e32 v38, s20, v3
	v_or_b32_e32 v4, s21, v30
	v_mov_b32_e32 v37, v5
	v_or_b32_e32 v36, s18, v3
	s_add_i32 s25, s19, 12
	v_lshlrev_b64 v[38:39], 15, v[38:39]
	v_lshlrev_b64 v[54:55], 15, v[4:5]
	v_or_b32_e32 v4, s23, v30
	s_add_i32 s22, s18, 8
	s_add_i32 s24, s18, 12
	s_add_i32 s27, s19, 16
	v_lshlrev_b64 v[36:37], 15, v[36:37]
	v_lshl_add_u64 v[52:53], v[28:29], 0, v[52:53]
	v_lshl_add_u64 v[38:39], v[28:29], 0, v[38:39]
	v_lshlrev_b64 v[56:57], 15, v[4:5]
	v_or_b32_e32 v4, s25, v30
	v_mov_b32_e32 v41, v5
	v_mov_b32_e32 v43, v5
	s_add_i32 s29, s19, 20
	v_or_b32_e32 v40, s22, v3
	v_or_b32_e32 v42, s24, v3
	v_lshl_add_u64 v[36:37], v[28:29], 0, v[36:37]
	v_lshl_add_u64 v[54:55], v[28:29], 0, v[54:55]
	global_load_dword v25, v[52:53], off
	global_load_dword v27, v[36:37], off
	global_load_dword v35, v[54:55], off
	global_load_dword v68, v[38:39], off
	v_lshlrev_b64 v[38:39], 15, v[4:5]
	v_or_b32_e32 v4, s27, v30
	s_add_i32 s26, s18, 16
	s_add_i32 s28, s18, 20
	s_add_i32 s31, s19, 24
	v_lshlrev_b64 v[40:41], 15, v[40:41]
	v_lshlrev_b64 v[42:43], 15, v[42:43]
	v_lshl_add_u64 v[36:37], v[28:29], 0, v[56:57]
	v_lshl_add_u64 v[38:39], v[28:29], 0, v[38:39]
	v_lshlrev_b64 v[52:53], 15, v[4:5]
	v_or_b32_e32 v4, s29, v30
	v_mov_b32_e32 v45, v5
	v_mov_b32_e32 v47, v5
	s_add_i32 s30, s18, 24
	s_add_i32 s33, s18, 28
	s_add_i32 s34, s19, 28
	v_or_b32_e32 v44, s26, v3
	v_or_b32_e32 v46, s28, v3
	v_lshl_add_u64 v[40:41], v[28:29], 0, v[40:41]
	v_lshl_add_u64 v[42:43], v[28:29], 0, v[42:43]
	global_load_dword v69, v[36:37], off
	global_load_dword v70, v[40:41], off
	global_load_dword v71, v[38:39], off
	global_load_dword v72, v[42:43], off
	v_lshlrev_b64 v[38:39], 15, v[4:5]
	v_or_b32_e32 v4, s31, v30
	v_mov_b32_e32 v49, v5
	v_mov_b32_e32 v51, v5
	v_or_b32_e32 v48, s30, v3
	v_or_b32_e32 v50, s33, v3
	v_lshlrev_b64 v[44:45], 15, v[44:45]
	v_lshlrev_b64 v[46:47], 15, v[46:47]
	v_lshl_add_u64 v[36:37], v[28:29], 0, v[52:53]
	v_lshl_add_u64 v[38:39], v[28:29], 0, v[38:39]
	v_lshlrev_b64 v[40:41], 15, v[4:5]
	v_or_b32_e32 v4, s34, v30
	v_lshlrev_b64 v[48:49], 15, v[48:49]
	v_lshlrev_b64 v[50:51], 15, v[50:51]
	v_lshl_add_u64 v[44:45], v[28:29], 0, v[44:45]
	v_lshl_add_u64 v[46:47], v[28:29], 0, v[46:47]
	global_load_dword v73, v[36:37], off
	global_load_dword v74, v[44:45], off
	global_load_dword v75, v[38:39], off
	global_load_dword v76, v[46:47], off
	v_lshl_add_u64 v[36:37], v[28:29], 0, v[40:41]
	v_lshlrev_b64 v[38:39], 15, v[4:5]
	v_lshl_add_u64 v[48:49], v[28:29], 0, v[48:49]
	v_lshl_add_u64 v[50:51], v[28:29], 0, v[50:51]
	v_lshl_add_u64 v[38:39], v[28:29], 0, v[38:39]
	global_load_dword v4, v[36:37], off
	global_load_dword v77, v[48:49], off
	global_load_dword v78, v[38:39], off
	global_load_dword v79, v[50:51], off
	v_or_b32_e32 v38, s18, v1
	v_or_b32_e32 v36, s19, v2
	s_add_i32 s12, s12, 16
	s_add_i32 s8, s8, 16
	s_add_i32 s13, s13, -16
	v_mad_u64_u32 v[36:37], vcc, v36, s17, v[6:7]
	v_mad_u64_u32 v[38:39], vcc, v38, s17, v[6:7]
	v_or_b32_e32 v37, s20, v1
	v_or_b32_e32 v39, s21, v2
	v_or_b32_e32 v46, s22, v1
	v_or_b32_e32 v44, s23, v2
	v_or_b32_e32 v50, s24, v1
	v_or_b32_e32 v48, s25, v2
	v_or_b32_e32 v54, s26, v1
	v_or_b32_e32 v52, s27, v2
	v_or_b32_e32 v58, s28, v1
	v_or_b32_e32 v56, s29, v2
	v_or_b32_e32 v62, s30, v1
	v_or_b32_e32 v60, s31, v2
	v_or_b32_e32 v66, s33, v1
	v_or_b32_e32 v64, s34, v2
	s_cmp_lg_u32 s13, 0
	v_mad_u64_u32 v[40:41], vcc, v39, s17, v[6:7]
	v_mad_u64_u32 v[42:43], vcc, v37, s17, v[6:7]
	v_mad_u64_u32 v[44:45], vcc, v44, s17, v[6:7]
	v_mad_u64_u32 v[46:47], vcc, v46, s17, v[6:7]
	v_mad_u64_u32 v[48:49], vcc, v48, s17, v[6:7]
	v_mad_u64_u32 v[50:51], vcc, v50, s17, v[6:7]
	v_mad_u64_u32 v[52:53], vcc, v52, s17, v[6:7]
	v_mad_u64_u32 v[54:55], vcc, v54, s17, v[6:7]
	v_mad_u64_u32 v[56:57], vcc, v56, s17, v[6:7]
	v_mad_u64_u32 v[58:59], vcc, v58, s17, v[6:7]
	v_mad_u64_u32 v[60:61], vcc, v60, s17, v[6:7]
	v_mad_u64_u32 v[62:63], vcc, v62, s17, v[6:7]
	v_mad_u64_u32 v[64:65], vcc, v64, s17, v[6:7]
	v_mad_u64_u32 v[66:67], vcc, v66, s17, v[6:7]
	s_nop 3
	v_mov_b32_e32 v181, v5
	s_lshl_b32 s18, s8, 1
	s_lshl_b32 s19, s12, 1
	v_or_b32_e32 v180, s19, v30
	s_add_i32 s20, s18, 4
	s_add_i32 s21, s19, 4
	v_mov_b32_e32 v139, v181
	s_add_i32 s23, s19, 8
	v_lshlrev_b64 v[152:153], 15, v[180:181]
	v_or_b32_e32 v138, s20, v3
	v_or_b32_e32 v180, s21, v30
	v_mov_b32_e32 v137, v181
	v_or_b32_e32 v136, s18, v3
	s_add_i32 s25, s19, 12
	v_lshlrev_b64 v[138:139], 15, v[138:139]
	v_lshlrev_b64 v[154:155], 15, v[180:181]
	v_or_b32_e32 v180, s23, v30
	s_add_i32 s22, s18, 8
	s_add_i32 s24, s18, 12
	s_add_i32 s27, s19, 16
	v_lshlrev_b64 v[136:137], 15, v[136:137]
	v_lshl_add_u64 v[152:153], v[28:29], 0, v[152:153]
	v_lshl_add_u64 v[138:139], v[28:29], 0, v[138:139]
	v_lshlrev_b64 v[156:157], 15, v[180:181]
	v_or_b32_e32 v180, s25, v30
	v_mov_b32_e32 v141, v181
	v_mov_b32_e32 v143, v181
	s_add_i32 s29, s19, 20
	v_or_b32_e32 v140, s22, v3
	v_or_b32_e32 v142, s24, v3
	v_lshl_add_u64 v[136:137], v[28:29], 0, v[136:137]
	v_lshl_add_u64 v[154:155], v[28:29], 0, v[154:155]
	global_load_dword v182, v[152:153], off
	global_load_dword v183, v[136:137], off
	global_load_dword v135, v[154:155], off
	global_load_dword v168, v[138:139], off
	v_lshlrev_b64 v[138:139], 15, v[180:181]
	v_or_b32_e32 v180, s27, v30
	s_add_i32 s26, s18, 16
	s_add_i32 s28, s18, 20
	s_add_i32 s31, s19, 24
	v_lshlrev_b64 v[140:141], 15, v[140:141]
	v_lshlrev_b64 v[142:143], 15, v[142:143]
	v_lshl_add_u64 v[136:137], v[28:29], 0, v[156:157]
	v_lshl_add_u64 v[138:139], v[28:29], 0, v[138:139]
	v_lshlrev_b64 v[152:153], 15, v[180:181]
	v_or_b32_e32 v180, s29, v30
	v_mov_b32_e32 v145, v181
	v_mov_b32_e32 v147, v181
	s_add_i32 s30, s18, 24
	s_add_i32 s33, s18, 28
	s_add_i32 s34, s19, 28
	v_or_b32_e32 v144, s26, v3
	v_or_b32_e32 v146, s28, v3
	v_lshl_add_u64 v[140:141], v[28:29], 0, v[140:141]
	v_lshl_add_u64 v[142:143], v[28:29], 0, v[142:143]
	global_load_dword v169, v[136:137], off
	global_load_dword v170, v[140:141], off
	global_load_dword v171, v[138:139], off
	global_load_dword v172, v[142:143], off
	v_lshlrev_b64 v[138:139], 15, v[180:181]
	v_or_b32_e32 v180, s31, v30
	v_mov_b32_e32 v149, v181
	v_mov_b32_e32 v151, v181
	v_or_b32_e32 v148, s30, v3
	v_or_b32_e32 v150, s33, v3
	v_lshlrev_b64 v[144:145], 15, v[144:145]
	v_lshlrev_b64 v[146:147], 15, v[146:147]
	v_lshl_add_u64 v[136:137], v[28:29], 0, v[152:153]
	v_lshl_add_u64 v[138:139], v[28:29], 0, v[138:139]
	v_lshlrev_b64 v[140:141], 15, v[180:181]
	v_or_b32_e32 v180, s34, v30
	v_lshlrev_b64 v[148:149], 15, v[148:149]
	v_lshlrev_b64 v[150:151], 15, v[150:151]
	v_lshl_add_u64 v[144:145], v[28:29], 0, v[144:145]
	v_lshl_add_u64 v[146:147], v[28:29], 0, v[146:147]
	global_load_dword v173, v[136:137], off
	global_load_dword v174, v[144:145], off
	global_load_dword v175, v[138:139], off
	global_load_dword v176, v[146:147], off
	v_lshl_add_u64 v[136:137], v[28:29], 0, v[140:141]
	v_lshlrev_b64 v[138:139], 15, v[180:181]
	v_lshl_add_u64 v[148:149], v[28:29], 0, v[148:149]
	v_lshl_add_u64 v[150:151], v[28:29], 0, v[150:151]
	v_lshl_add_u64 v[138:139], v[28:29], 0, v[138:139]
	global_load_dword v180, v[136:137], off
	global_load_dword v177, v[148:149], off
	global_load_dword v178, v[138:139], off
	global_load_dword v179, v[150:151], off
	s_waitcnt vmcnt(31)
	ds_write_b32 v36, v25
	s_waitcnt vmcnt(30)
	ds_write_b32 v38, v27
	s_waitcnt vmcnt(29)
	ds_write_b32 v40, v35
	s_waitcnt vmcnt(28)
	ds_write_b32 v42, v68
	s_waitcnt vmcnt(27)
	ds_write_b32 v44, v69
	s_waitcnt vmcnt(26)
	ds_write_b32 v46, v70
	s_waitcnt vmcnt(25)
	ds_write_b32 v48, v71
	s_waitcnt vmcnt(24)
	ds_write_b32 v50, v72
	s_waitcnt vmcnt(23)
	ds_write_b32 v52, v73
	s_waitcnt vmcnt(22)
	ds_write_b32 v54, v74
	s_waitcnt vmcnt(21)
	ds_write_b32 v56, v75
	s_waitcnt vmcnt(20)
	ds_write_b32 v58, v76
	s_waitcnt vmcnt(19)
	ds_write_b32 v60, v4
	s_waitcnt vmcnt(18)
	ds_write_b32 v62, v77
	s_waitcnt vmcnt(17)
	ds_write_b32 v64, v78
	s_waitcnt vmcnt(16)
	ds_write_b32 v66, v79
	v_or_b32_e32 v138, s18, v1
	v_or_b32_e32 v136, s19, v2
	s_add_i32 s12, s12, 16
	s_add_i32 s8, s8, 16
	s_add_i32 s13, s13, -16
	v_mad_u64_u32 v[136:137], vcc, v136, s17, v[6:7]
	v_mad_u64_u32 v[138:139], vcc, v138, s17, v[6:7]
	v_or_b32_e32 v137, s20, v1
	v_or_b32_e32 v139, s21, v2
	v_or_b32_e32 v146, s22, v1
	v_or_b32_e32 v144, s23, v2
	v_or_b32_e32 v150, s24, v1
	v_or_b32_e32 v148, s25, v2
	v_or_b32_e32 v154, s26, v1
	v_or_b32_e32 v152, s27, v2
	v_or_b32_e32 v158, s28, v1
	v_or_b32_e32 v156, s29, v2
	v_or_b32_e32 v162, s30, v1
	v_or_b32_e32 v160, s31, v2
	v_or_b32_e32 v166, s33, v1
	v_or_b32_e32 v164, s34, v2
	s_cmp_lg_u32 s13, 0
	v_mad_u64_u32 v[140:141], vcc, v139, s17, v[6:7]
	v_mad_u64_u32 v[142:143], vcc, v137, s17, v[6:7]
	v_mad_u64_u32 v[144:145], vcc, v144, s17, v[6:7]
	v_mad_u64_u32 v[146:147], vcc, v146, s17, v[6:7]
	v_mad_u64_u32 v[148:149], vcc, v148, s17, v[6:7]
	v_mad_u64_u32 v[150:151], vcc, v150, s17, v[6:7]
	v_mad_u64_u32 v[152:153], vcc, v152, s17, v[6:7]
	v_mad_u64_u32 v[154:155], vcc, v154, s17, v[6:7]
	v_mad_u64_u32 v[156:157], vcc, v156, s17, v[6:7]
	v_mad_u64_u32 v[158:159], vcc, v158, s17, v[6:7]
	v_mad_u64_u32 v[160:161], vcc, v160, s17, v[6:7]
	v_mad_u64_u32 v[162:163], vcc, v162, s17, v[6:7]
	v_mad_u64_u32 v[164:165], vcc, v164, s17, v[6:7]
	v_mad_u64_u32 v[166:167], vcc, v166, s17, v[6:7]
	s_waitcnt vmcnt(15)
	ds_write_b32 v136, v182
	s_waitcnt vmcnt(14)
	ds_write_b32 v138, v183
	s_waitcnt vmcnt(13)
	ds_write_b32 v140, v135
	s_waitcnt vmcnt(12)
	ds_write_b32 v142, v168
	s_waitcnt vmcnt(11)
	ds_write_b32 v144, v169
	s_waitcnt vmcnt(10)
	ds_write_b32 v146, v170
	s_waitcnt vmcnt(9)
	ds_write_b32 v148, v171
	s_waitcnt vmcnt(8)
	ds_write_b32 v150, v172
	s_waitcnt vmcnt(7)
	ds_write_b32 v152, v173
	s_waitcnt vmcnt(6)
	ds_write_b32 v154, v174
	s_waitcnt vmcnt(5)
	ds_write_b32 v156, v175
	s_waitcnt vmcnt(4)
	ds_write_b32 v158, v176
	s_waitcnt vmcnt(3)
	ds_write_b32 v160, v180
	s_waitcnt vmcnt(2)
	ds_write_b32 v162, v177
	s_waitcnt vmcnt(1)
	ds_write_b32 v164, v178
	s_waitcnt vmcnt(0)
	ds_write_b32 v166, v179
	s_waitcnt lgkmcnt(0)
	ds_read2_b32 v[40:41], v31 offset0:33 offset1:41
	ds_read2_b32 v[42:43], v31 offset1:8
	ds_read2_b32 v[44:45], v31 offset0:66 offset1:74
	ds_read2_b32 v[46:47], v31 offset0:99 offset1:107
	ds_read2_b32 v[48:49], v31 offset0:132 offset1:140
	ds_read2_b32 v[50:51], v31 offset0:165 offset1:173
	ds_read2_b32 v[52:53], v31 offset0:198 offset1:206
	ds_read2_b32 v[54:55], v31 offset0:231 offset1:239
	v_lshl_add_u64 v[28:29], s[4:5], 1, v[10:11]
	s_lshl_b32 s8, s3, 1
	v_lshl_add_u64 v[28:29], v[28:29], 0, s[8:9]
	v_mov_b32_e32 v27, v5
	v_or_b32_e32 v3, s2, v7
	v_lshl_add_u64 v[28:29], v[28:29], 0, v[26:27]
	v_lshlrev_b32_e32 v4, 12, v3
	s_waitcnt lgkmcnt(6)
	v_cvt_pk_bf16_f32 v36, v42, v40
	s_waitcnt lgkmcnt(4)
	v_cvt_pk_bf16_f32 v37, v44, v46
	s_waitcnt lgkmcnt(2)
	v_cvt_pk_bf16_f32 v38, v48, v50
	s_waitcnt lgkmcnt(0)
	v_cvt_pk_bf16_f32 v39, v52, v54
	v_lshl_add_u64 v[56:57], v[28:29], 0, v[4:5]
	global_store_dwordx4 v[56:57], v[36:39], off
	v_or_b32_e32 v3, s2, v32
	v_lshlrev_b32_e32 v4, 12, v3
	v_cvt_pk_bf16_f32 v36, v43, v41
	v_cvt_pk_bf16_f32 v37, v45, v47
	v_cvt_pk_bf16_f32 v38, v49, v51
	v_cvt_pk_bf16_f32 v39, v53, v55
	ds_read2_b32 v[42:43], v31 offset0:49 offset1:57
	ds_read2_b32 v[44:45], v31 offset0:16 offset1:24
	ds_read2_b32 v[46:47], v31 offset0:82 offset1:90
	ds_read2_b32 v[48:49], v31 offset0:115 offset1:123
	ds_read2_b32 v[50:51], v31 offset0:148 offset1:156
	ds_read2_b32 v[52:53], v31 offset0:181 offset1:189
	ds_read2_b32 v[54:55], v31 offset0:214 offset1:222
	ds_read2_b32 v[56:57], v31 offset0:247 offset1:255
	v_or_b32_e32 v3, s2, v33
	v_lshl_add_u64 v[40:41], v[28:29], 0, v[4:5]
	v_lshlrev_b32_e32 v4, 12, v3
	v_or_b32_e32 v3, s2, v34
	global_store_dwordx4 v[40:41], v[36:39], off
	v_lshl_add_u64 v[40:41], v[28:29], 0, v[4:5]
	v_lshlrev_b32_e32 v4, 12, v3
	s_waitcnt lgkmcnt(6)
	v_cvt_pk_bf16_f32 v36, v44, v42
	s_waitcnt lgkmcnt(4)
	v_cvt_pk_bf16_f32 v37, v46, v48
	s_waitcnt lgkmcnt(2)
	v_cvt_pk_bf16_f32 v38, v50, v52
	s_waitcnt lgkmcnt(0)
	v_cvt_pk_bf16_f32 v39, v54, v56
	global_store_dwordx4 v[40:41], v[36:39], off
	v_lshl_add_u64 v[28:29], v[28:29], 0, v[4:5]
	s_nop 0
	v_cvt_pk_bf16_f32 v36, v45, v43
	v_cvt_pk_bf16_f32 v37, v47, v49
	v_cvt_pk_bf16_f32 v38, v51, v53
	v_cvt_pk_bf16_f32 v39, v55, v57
	global_store_dwordx4 v[28:29], v[36:39], off
	s_waitcnt lgkmcnt(0)

.LBB0_130:
	s_lshl_b32 s13, s3, 1
	s_lshl_b32 s18, s8, 1
	v_or_b32_e32 v4, s18, v30
	s_add_i32 s20, s13, 4
	s_add_i32 s21, s18, 4
	v_mov_b32_e32 v39, v5
	s_add_i32 s23, s18, 8
	v_lshlrev_b64 v[52:53], 14, v[4:5]
	v_or_b32_e32 v38, s20, v3
	v_or_b32_e32 v4, s21, v30
	v_mov_b32_e32 v37, v5
	v_or_b32_e32 v36, s13, v3
	s_add_i32 s25, s18, 12
	v_lshlrev_b64 v[38:39], 14, v[38:39]
	v_lshlrev_b64 v[54:55], 14, v[4:5]
	v_or_b32_e32 v4, s23, v30
	s_add_i32 s22, s13, 8
	s_add_i32 s24, s13, 12
	s_add_i32 s27, s18, 16
	v_lshlrev_b64 v[36:37], 14, v[36:37]
	v_lshl_add_u64 v[52:53], v[28:29], 0, v[52:53]
	v_lshl_add_u64 v[38:39], v[28:29], 0, v[38:39]
	v_lshlrev_b64 v[56:57], 14, v[4:5]
	v_or_b32_e32 v4, s25, v30
	v_mov_b32_e32 v41, v5
	v_mov_b32_e32 v43, v5
	s_add_i32 s29, s18, 20
	v_or_b32_e32 v40, s22, v3
	v_or_b32_e32 v42, s24, v3
	v_lshl_add_u64 v[36:37], v[28:29], 0, v[36:37]
	v_lshl_add_u64 v[54:55], v[28:29], 0, v[54:55]
	global_load_dword v25, v[52:53], off
	global_load_dword v27, v[36:37], off
	global_load_dword v35, v[54:55], off
	global_load_dword v68, v[38:39], off
	v_lshlrev_b64 v[38:39], 14, v[4:5]
	v_or_b32_e32 v4, s27, v30
	s_add_i32 s26, s13, 16
	s_add_i32 s28, s13, 20
	s_add_i32 s31, s18, 24
	v_lshlrev_b64 v[40:41], 14, v[40:41]
	v_lshlrev_b64 v[42:43], 14, v[42:43]
	v_lshl_add_u64 v[36:37], v[28:29], 0, v[56:57]
	v_lshl_add_u64 v[38:39], v[28:29], 0, v[38:39]
	v_lshlrev_b64 v[52:53], 14, v[4:5]
	v_or_b32_e32 v4, s29, v30
	v_mov_b32_e32 v45, v5
	v_mov_b32_e32 v47, v5
	s_add_i32 s30, s13, 24
	s_add_i32 s33, s13, 28
	s_add_i32 s34, s18, 28
	v_or_b32_e32 v44, s26, v3
	v_or_b32_e32 v46, s28, v3
	v_lshl_add_u64 v[40:41], v[28:29], 0, v[40:41]
	v_lshl_add_u64 v[42:43], v[28:29], 0, v[42:43]
	global_load_dword v69, v[36:37], off
	global_load_dword v70, v[40:41], off
	global_load_dword v71, v[38:39], off
	global_load_dword v72, v[42:43], off
	v_lshlrev_b64 v[38:39], 14, v[4:5]
	v_or_b32_e32 v4, s31, v30
	v_mov_b32_e32 v49, v5
	v_mov_b32_e32 v51, v5
	v_or_b32_e32 v48, s30, v3
	v_or_b32_e32 v50, s33, v3
	v_lshlrev_b64 v[44:45], 14, v[44:45]
	v_lshlrev_b64 v[46:47], 14, v[46:47]
	v_lshl_add_u64 v[36:37], v[28:29], 0, v[52:53]
	v_lshl_add_u64 v[38:39], v[28:29], 0, v[38:39]
	v_lshlrev_b64 v[40:41], 14, v[4:5]
	v_or_b32_e32 v4, s34, v30
	v_lshlrev_b64 v[48:49], 14, v[48:49]
	v_lshlrev_b64 v[50:51], 14, v[50:51]
	v_lshl_add_u64 v[44:45], v[28:29], 0, v[44:45]
	v_lshl_add_u64 v[46:47], v[28:29], 0, v[46:47]
	global_load_dword v73, v[36:37], off
	global_load_dword v74, v[44:45], off
	global_load_dword v75, v[38:39], off
	global_load_dword v76, v[46:47], off
	v_lshl_add_u64 v[36:37], v[28:29], 0, v[40:41]
	v_lshlrev_b64 v[38:39], 14, v[4:5]
	v_lshl_add_u64 v[48:49], v[28:29], 0, v[48:49]
	v_lshl_add_u64 v[50:51], v[28:29], 0, v[50:51]
	v_lshl_add_u64 v[38:39], v[28:29], 0, v[38:39]
	global_load_dword v4, v[36:37], off
	global_load_dword v77, v[48:49], off
	global_load_dword v78, v[38:39], off
	global_load_dword v79, v[50:51], off
	v_or_b32_e32 v38, s13, v1
	v_or_b32_e32 v36, s18, v2
	s_add_i32 s8, s8, 16
	s_add_i32 s3, s3, 16
	s_add_i32 s12, s12, -16
	v_mad_u64_u32 v[36:37], vcc, v36, s17, v[6:7]
	v_mad_u64_u32 v[38:39], vcc, v38, s17, v[6:7]
	v_or_b32_e32 v37, s20, v1
	v_or_b32_e32 v39, s21, v2
	v_or_b32_e32 v46, s22, v1
	v_or_b32_e32 v44, s23, v2
	v_or_b32_e32 v50, s24, v1
	v_or_b32_e32 v48, s25, v2
	v_or_b32_e32 v54, s26, v1
	v_or_b32_e32 v52, s27, v2
	v_or_b32_e32 v58, s28, v1
	v_or_b32_e32 v56, s29, v2
	v_or_b32_e32 v62, s30, v1
	v_or_b32_e32 v60, s31, v2
	v_or_b32_e32 v66, s33, v1
	v_or_b32_e32 v64, s34, v2
	s_cmp_lg_u32 s12, 0
	v_mad_u64_u32 v[40:41], vcc, v39, s17, v[6:7]
	v_mad_u64_u32 v[42:43], vcc, v37, s17, v[6:7]
	v_mad_u64_u32 v[44:45], vcc, v44, s17, v[6:7]
	v_mad_u64_u32 v[46:47], vcc, v46, s17, v[6:7]
	v_mad_u64_u32 v[48:49], vcc, v48, s17, v[6:7]
	v_mad_u64_u32 v[50:51], vcc, v50, s17, v[6:7]
	v_mad_u64_u32 v[52:53], vcc, v52, s17, v[6:7]
	v_mad_u64_u32 v[54:55], vcc, v54, s17, v[6:7]
	v_mad_u64_u32 v[56:57], vcc, v56, s17, v[6:7]
	v_mad_u64_u32 v[58:59], vcc, v58, s17, v[6:7]
	v_mad_u64_u32 v[60:61], vcc, v60, s17, v[6:7]
	v_mad_u64_u32 v[62:63], vcc, v62, s17, v[6:7]
	v_mad_u64_u32 v[64:65], vcc, v64, s17, v[6:7]
	v_mad_u64_u32 v[66:67], vcc, v66, s17, v[6:7]
	s_nop 3
	v_mov_b32_e32 v181, v5
	s_lshl_b32 s13, s3, 1
	s_lshl_b32 s18, s8, 1
	v_or_b32_e32 v180, s18, v30
	s_add_i32 s20, s13, 4
	s_add_i32 s21, s18, 4
	v_mov_b32_e32 v139, v181
	s_add_i32 s23, s18, 8
	v_lshlrev_b64 v[152:153], 14, v[180:181]
	v_or_b32_e32 v138, s20, v3
	v_or_b32_e32 v180, s21, v30
	v_mov_b32_e32 v137, v181
	v_or_b32_e32 v136, s13, v3
	s_add_i32 s25, s18, 12
	v_lshlrev_b64 v[138:139], 14, v[138:139]
	v_lshlrev_b64 v[154:155], 14, v[180:181]
	v_or_b32_e32 v180, s23, v30
	s_add_i32 s22, s13, 8
	s_add_i32 s24, s13, 12
	s_add_i32 s27, s18, 16
	v_lshlrev_b64 v[136:137], 14, v[136:137]
	v_lshl_add_u64 v[152:153], v[28:29], 0, v[152:153]
	v_lshl_add_u64 v[138:139], v[28:29], 0, v[138:139]
	v_lshlrev_b64 v[156:157], 14, v[180:181]
	v_or_b32_e32 v180, s25, v30
	v_mov_b32_e32 v141, v181
	v_mov_b32_e32 v143, v181
	s_add_i32 s29, s18, 20
	v_or_b32_e32 v140, s22, v3
	v_or_b32_e32 v142, s24, v3
	v_lshl_add_u64 v[136:137], v[28:29], 0, v[136:137]
	v_lshl_add_u64 v[154:155], v[28:29], 0, v[154:155]
	global_load_dword v182, v[152:153], off
	global_load_dword v183, v[136:137], off
	global_load_dword v135, v[154:155], off
	global_load_dword v168, v[138:139], off
	v_lshlrev_b64 v[138:139], 14, v[180:181]
	v_or_b32_e32 v180, s27, v30
	s_add_i32 s26, s13, 16
	s_add_i32 s28, s13, 20
	s_add_i32 s31, s18, 24
	v_lshlrev_b64 v[140:141], 14, v[140:141]
	v_lshlrev_b64 v[142:143], 14, v[142:143]
	v_lshl_add_u64 v[136:137], v[28:29], 0, v[156:157]
	v_lshl_add_u64 v[138:139], v[28:29], 0, v[138:139]
	v_lshlrev_b64 v[152:153], 14, v[180:181]
	v_or_b32_e32 v180, s29, v30
	v_mov_b32_e32 v145, v181
	v_mov_b32_e32 v147, v181
	s_add_i32 s30, s13, 24
	s_add_i32 s33, s13, 28
	s_add_i32 s34, s18, 28
	v_or_b32_e32 v144, s26, v3
	v_or_b32_e32 v146, s28, v3
	v_lshl_add_u64 v[140:141], v[28:29], 0, v[140:141]
	v_lshl_add_u64 v[142:143], v[28:29], 0, v[142:143]
	global_load_dword v169, v[136:137], off
	global_load_dword v170, v[140:141], off
	global_load_dword v171, v[138:139], off
	global_load_dword v172, v[142:143], off
	v_lshlrev_b64 v[138:139], 14, v[180:181]
	v_or_b32_e32 v180, s31, v30
	v_mov_b32_e32 v149, v181
	v_mov_b32_e32 v151, v181
	v_or_b32_e32 v148, s30, v3
	v_or_b32_e32 v150, s33, v3
	v_lshlrev_b64 v[144:145], 14, v[144:145]
	v_lshlrev_b64 v[146:147], 14, v[146:147]
	v_lshl_add_u64 v[136:137], v[28:29], 0, v[152:153]
	v_lshl_add_u64 v[138:139], v[28:29], 0, v[138:139]
	v_lshlrev_b64 v[140:141], 14, v[180:181]
	v_or_b32_e32 v180, s34, v30
	v_lshlrev_b64 v[148:149], 14, v[148:149]
	v_lshlrev_b64 v[150:151], 14, v[150:151]
	v_lshl_add_u64 v[144:145], v[28:29], 0, v[144:145]
	v_lshl_add_u64 v[146:147], v[28:29], 0, v[146:147]
	global_load_dword v173, v[136:137], off
	global_load_dword v174, v[144:145], off
	global_load_dword v175, v[138:139], off
	global_load_dword v176, v[146:147], off
	v_lshl_add_u64 v[136:137], v[28:29], 0, v[140:141]
	v_lshlrev_b64 v[138:139], 14, v[180:181]
	v_lshl_add_u64 v[148:149], v[28:29], 0, v[148:149]
	v_lshl_add_u64 v[150:151], v[28:29], 0, v[150:151]
	v_lshl_add_u64 v[138:139], v[28:29], 0, v[138:139]
	global_load_dword v180, v[136:137], off
	global_load_dword v177, v[148:149], off
	global_load_dword v178, v[138:139], off
	global_load_dword v179, v[150:151], off
	s_waitcnt vmcnt(31)
	ds_write_b32 v36, v25
	s_waitcnt vmcnt(30)
	ds_write_b32 v38, v27
	s_waitcnt vmcnt(29)
	ds_write_b32 v40, v35
	s_waitcnt vmcnt(28)
	ds_write_b32 v42, v68
	s_waitcnt vmcnt(27)
	ds_write_b32 v44, v69
	s_waitcnt vmcnt(26)
	ds_write_b32 v46, v70
	s_waitcnt vmcnt(25)
	ds_write_b32 v48, v71
	s_waitcnt vmcnt(24)
	ds_write_b32 v50, v72
	s_waitcnt vmcnt(23)
	ds_write_b32 v52, v73
	s_waitcnt vmcnt(22)
	ds_write_b32 v54, v74
	s_waitcnt vmcnt(21)
	ds_write_b32 v56, v75
	s_waitcnt vmcnt(20)
	ds_write_b32 v58, v76
	s_waitcnt vmcnt(19)
	ds_write_b32 v60, v4
	s_waitcnt vmcnt(18)
	ds_write_b32 v62, v77
	s_waitcnt vmcnt(17)
	ds_write_b32 v64, v78
	s_waitcnt vmcnt(16)
	ds_write_b32 v66, v79
	v_or_b32_e32 v138, s13, v1
	v_or_b32_e32 v136, s18, v2
	s_add_i32 s8, s8, 16
	s_add_i32 s3, s3, 16
	s_add_i32 s12, s12, -16
	v_mad_u64_u32 v[136:137], vcc, v136, s17, v[6:7]
	v_mad_u64_u32 v[138:139], vcc, v138, s17, v[6:7]
	v_or_b32_e32 v137, s20, v1
	v_or_b32_e32 v139, s21, v2
	v_or_b32_e32 v146, s22, v1
	v_or_b32_e32 v144, s23, v2
	v_or_b32_e32 v150, s24, v1
	v_or_b32_e32 v148, s25, v2
	v_or_b32_e32 v154, s26, v1
	v_or_b32_e32 v152, s27, v2
	v_or_b32_e32 v158, s28, v1
	v_or_b32_e32 v156, s29, v2
	v_or_b32_e32 v162, s30, v1
	v_or_b32_e32 v160, s31, v2
	v_or_b32_e32 v166, s33, v1
	v_or_b32_e32 v164, s34, v2
	s_cmp_lg_u32 s12, 0
	v_mad_u64_u32 v[140:141], vcc, v139, s17, v[6:7]
	v_mad_u64_u32 v[142:143], vcc, v137, s17, v[6:7]
	v_mad_u64_u32 v[144:145], vcc, v144, s17, v[6:7]
	v_mad_u64_u32 v[146:147], vcc, v146, s17, v[6:7]
	v_mad_u64_u32 v[148:149], vcc, v148, s17, v[6:7]
	v_mad_u64_u32 v[150:151], vcc, v150, s17, v[6:7]
	v_mad_u64_u32 v[152:153], vcc, v152, s17, v[6:7]
	v_mad_u64_u32 v[154:155], vcc, v154, s17, v[6:7]
	v_mad_u64_u32 v[156:157], vcc, v156, s17, v[6:7]
	v_mad_u64_u32 v[158:159], vcc, v158, s17, v[6:7]
	v_mad_u64_u32 v[160:161], vcc, v160, s17, v[6:7]
	v_mad_u64_u32 v[162:163], vcc, v162, s17, v[6:7]
	v_mad_u64_u32 v[164:165], vcc, v164, s17, v[6:7]
	v_mad_u64_u32 v[166:167], vcc, v166, s17, v[6:7]
	s_waitcnt vmcnt(15)
	ds_write_b32 v136, v182
	s_waitcnt vmcnt(14)
	ds_write_b32 v138, v183
	s_waitcnt vmcnt(13)
	ds_write_b32 v140, v135
	s_waitcnt vmcnt(12)
	ds_write_b32 v142, v168
	s_waitcnt vmcnt(11)
	ds_write_b32 v144, v169
	s_waitcnt vmcnt(10)
	ds_write_b32 v146, v170
	s_waitcnt vmcnt(9)
	ds_write_b32 v148, v171
	s_waitcnt vmcnt(8)
	ds_write_b32 v150, v172
	s_waitcnt vmcnt(7)
	ds_write_b32 v152, v173
	s_waitcnt vmcnt(6)
	ds_write_b32 v154, v174
	s_waitcnt vmcnt(5)
	ds_write_b32 v156, v175
	s_waitcnt vmcnt(4)
	ds_write_b32 v158, v176
	s_waitcnt vmcnt(3)
	ds_write_b32 v160, v180
	s_waitcnt vmcnt(2)
	ds_write_b32 v162, v177
	s_waitcnt vmcnt(1)
	ds_write_b32 v164, v178
	s_waitcnt vmcnt(0)
	ds_write_b32 v166, v179
	s_waitcnt lgkmcnt(0)
	s_lshl_b32 s8, s2, 6
	s_cmp_gt_u32 s2, 63
	s_mov_b64 s[2:3], -1
	s_cbranch_scc0 .LBB0_133
	s_add_i32 s2, s8, 0x7ffff000
	s_and_b32 s2, s2, 0x7fffff00
	s_and_b32 s3, s5, 0x60
	s_or_b32 s2, s3, s2
	s_or_b32 s12, s2, 0x80
	s_mov_b64 s[2:3], 0

.LBB0_139:
	s_lshl_b32 s12, s4, 1
	s_lshl_b32 s13, s5, 1
	v_or_b32_e32 v4, s13, v30
	s_add_i32 s18, s12, 4
	s_add_i32 s19, s13, 4
	v_mov_b32_e32 v39, v5
	s_add_i32 s21, s13, 8
	v_lshlrev_b64 v[52:53], 13, v[4:5]
	v_or_b32_e32 v38, s18, v3
	v_or_b32_e32 v4, s19, v30
	v_mov_b32_e32 v37, v5
	v_or_b32_e32 v36, s12, v3
	s_add_i32 s23, s13, 12
	v_lshlrev_b64 v[38:39], 13, v[38:39]
	v_lshlrev_b64 v[54:55], 13, v[4:5]
	v_or_b32_e32 v4, s21, v30
	s_add_i32 s20, s12, 8
	s_add_i32 s22, s12, 12
	s_add_i32 s25, s13, 16
	v_lshlrev_b64 v[36:37], 13, v[36:37]
	v_lshl_add_u64 v[52:53], v[28:29], 0, v[52:53]
	v_lshl_add_u64 v[38:39], v[28:29], 0, v[38:39]
	v_lshlrev_b64 v[56:57], 13, v[4:5]
	v_or_b32_e32 v4, s23, v30
	v_mov_b32_e32 v41, v5
	v_mov_b32_e32 v43, v5
	s_add_i32 s27, s13, 20
	v_or_b32_e32 v40, s20, v3
	v_or_b32_e32 v42, s22, v3
	v_lshl_add_u64 v[36:37], v[28:29], 0, v[36:37]
	v_lshl_add_u64 v[54:55], v[28:29], 0, v[54:55]
	global_load_dword v25, v[52:53], off
	global_load_dword v27, v[36:37], off
	global_load_dword v35, v[54:55], off
	global_load_dword v68, v[38:39], off
	v_lshlrev_b64 v[38:39], 13, v[4:5]
	v_or_b32_e32 v4, s25, v30
	s_add_i32 s24, s12, 16
	s_add_i32 s26, s12, 20
	s_add_i32 s29, s13, 24
	v_lshlrev_b64 v[40:41], 13, v[40:41]
	v_lshlrev_b64 v[42:43], 13, v[42:43]
	v_lshl_add_u64 v[36:37], v[28:29], 0, v[56:57]
	v_lshl_add_u64 v[38:39], v[28:29], 0, v[38:39]
	v_lshlrev_b64 v[52:53], 13, v[4:5]
	v_or_b32_e32 v4, s27, v30
	v_mov_b32_e32 v45, v5
	v_mov_b32_e32 v47, v5
	s_add_i32 s28, s12, 24
	s_add_i32 s30, s12, 28
	s_add_i32 s31, s13, 28
	v_or_b32_e32 v44, s24, v3
	v_or_b32_e32 v46, s26, v3
	v_lshl_add_u64 v[40:41], v[28:29], 0, v[40:41]
	v_lshl_add_u64 v[42:43], v[28:29], 0, v[42:43]
	global_load_dword v69, v[36:37], off
	global_load_dword v70, v[40:41], off
	global_load_dword v71, v[38:39], off
	global_load_dword v72, v[42:43], off
	v_lshlrev_b64 v[38:39], 13, v[4:5]
	v_or_b32_e32 v4, s29, v30
	v_mov_b32_e32 v49, v5
	v_mov_b32_e32 v51, v5
	v_or_b32_e32 v48, s28, v3
	v_or_b32_e32 v50, s30, v3
	v_lshlrev_b64 v[44:45], 13, v[44:45]
	v_lshlrev_b64 v[46:47], 13, v[46:47]
	v_lshl_add_u64 v[36:37], v[28:29], 0, v[52:53]
	v_lshl_add_u64 v[38:39], v[28:29], 0, v[38:39]
	v_lshlrev_b64 v[40:41], 13, v[4:5]
	v_or_b32_e32 v4, s31, v30
	v_lshlrev_b64 v[48:49], 13, v[48:49]
	v_lshlrev_b64 v[50:51], 13, v[50:51]
	v_lshl_add_u64 v[44:45], v[28:29], 0, v[44:45]
	v_lshl_add_u64 v[46:47], v[28:29], 0, v[46:47]
	global_load_dword v73, v[36:37], off
	global_load_dword v74, v[44:45], off
	global_load_dword v75, v[38:39], off
	global_load_dword v76, v[46:47], off
	v_lshl_add_u64 v[36:37], v[28:29], 0, v[40:41]
	v_lshlrev_b64 v[38:39], 13, v[4:5]
	v_lshl_add_u64 v[48:49], v[28:29], 0, v[48:49]
	v_lshl_add_u64 v[50:51], v[28:29], 0, v[50:51]
	v_lshl_add_u64 v[38:39], v[28:29], 0, v[38:39]
	global_load_dword v4, v[36:37], off
	global_load_dword v77, v[48:49], off
	global_load_dword v78, v[38:39], off
	global_load_dword v79, v[50:51], off
	v_or_b32_e32 v38, s12, v1
	v_or_b32_e32 v36, s13, v2
	s_add_i32 s5, s5, 16
	s_add_i32 s4, s4, 16
	s_add_i32 s8, s8, -16
	v_mad_u64_u32 v[36:37], vcc, v36, s17, v[6:7]
	v_mad_u64_u32 v[38:39], vcc, v38, s17, v[6:7]
	v_or_b32_e32 v37, s18, v1
	v_or_b32_e32 v39, s19, v2
	v_or_b32_e32 v46, s20, v1
	v_or_b32_e32 v44, s21, v2
	v_or_b32_e32 v50, s22, v1
	v_or_b32_e32 v48, s23, v2
	v_or_b32_e32 v54, s24, v1
	v_or_b32_e32 v52, s25, v2
	v_or_b32_e32 v58, s26, v1
	v_or_b32_e32 v56, s27, v2
	v_or_b32_e32 v62, s28, v1
	v_or_b32_e32 v60, s29, v2
	v_or_b32_e32 v66, s30, v1
	v_or_b32_e32 v64, s31, v2
	s_cmp_lg_u32 s8, 0
	v_mad_u64_u32 v[40:41], vcc, v39, s17, v[6:7]
	v_mad_u64_u32 v[42:43], vcc, v37, s17, v[6:7]
	v_mad_u64_u32 v[44:45], vcc, v44, s17, v[6:7]
	v_mad_u64_u32 v[46:47], vcc, v46, s17, v[6:7]
	v_mad_u64_u32 v[48:49], vcc, v48, s17, v[6:7]
	v_mad_u64_u32 v[50:51], vcc, v50, s17, v[6:7]
	v_mad_u64_u32 v[52:53], vcc, v52, s17, v[6:7]
	v_mad_u64_u32 v[54:55], vcc, v54, s17, v[6:7]
	v_mad_u64_u32 v[56:57], vcc, v56, s17, v[6:7]
	v_mad_u64_u32 v[58:59], vcc, v58, s17, v[6:7]
	v_mad_u64_u32 v[60:61], vcc, v60, s17, v[6:7]
	v_mad_u64_u32 v[62:63], vcc, v62, s17, v[6:7]
	v_mad_u64_u32 v[64:65], vcc, v64, s17, v[6:7]
	v_mad_u64_u32 v[66:67], vcc, v66, s17, v[6:7]
	s_nop 3
	v_mov_b32_e32 v181, v5
	s_lshl_b32 s12, s4, 1
	s_lshl_b32 s13, s5, 1
	v_or_b32_e32 v180, s13, v30
	s_add_i32 s18, s12, 4
	s_add_i32 s19, s13, 4
	v_mov_b32_e32 v139, v181
	s_add_i32 s21, s13, 8
	v_lshlrev_b64 v[152:153], 13, v[180:181]
	v_or_b32_e32 v138, s18, v3
	v_or_b32_e32 v180, s19, v30
	v_mov_b32_e32 v137, v181
	v_or_b32_e32 v136, s12, v3
	s_add_i32 s23, s13, 12
	v_lshlrev_b64 v[138:139], 13, v[138:139]
	v_lshlrev_b64 v[154:155], 13, v[180:181]
	v_or_b32_e32 v180, s21, v30
	s_add_i32 s20, s12, 8
	s_add_i32 s22, s12, 12
	s_add_i32 s25, s13, 16
	v_lshlrev_b64 v[136:137], 13, v[136:137]
	v_lshl_add_u64 v[152:153], v[28:29], 0, v[152:153]
	v_lshl_add_u64 v[138:139], v[28:29], 0, v[138:139]
	v_lshlrev_b64 v[156:157], 13, v[180:181]
	v_or_b32_e32 v180, s23, v30
	v_mov_b32_e32 v141, v181
	v_mov_b32_e32 v143, v181
	s_add_i32 s27, s13, 20
	v_or_b32_e32 v140, s20, v3
	v_or_b32_e32 v142, s22, v3
	v_lshl_add_u64 v[136:137], v[28:29], 0, v[136:137]
	v_lshl_add_u64 v[154:155], v[28:29], 0, v[154:155]
	global_load_dword v182, v[152:153], off
	global_load_dword v183, v[136:137], off
	global_load_dword v135, v[154:155], off
	global_load_dword v168, v[138:139], off
	v_lshlrev_b64 v[138:139], 13, v[180:181]
	v_or_b32_e32 v180, s25, v30
	s_add_i32 s24, s12, 16
	s_add_i32 s26, s12, 20
	s_add_i32 s29, s13, 24
	v_lshlrev_b64 v[140:141], 13, v[140:141]
	v_lshlrev_b64 v[142:143], 13, v[142:143]
	v_lshl_add_u64 v[136:137], v[28:29], 0, v[156:157]
	v_lshl_add_u64 v[138:139], v[28:29], 0, v[138:139]
	v_lshlrev_b64 v[152:153], 13, v[180:181]
	v_or_b32_e32 v180, s27, v30
	v_mov_b32_e32 v145, v181
	v_mov_b32_e32 v147, v181
	s_add_i32 s28, s12, 24
	s_add_i32 s30, s12, 28
	s_add_i32 s31, s13, 28
	v_or_b32_e32 v144, s24, v3
	v_or_b32_e32 v146, s26, v3
	v_lshl_add_u64 v[140:141], v[28:29], 0, v[140:141]
	v_lshl_add_u64 v[142:143], v[28:29], 0, v[142:143]
	global_load_dword v169, v[136:137], off
	global_load_dword v170, v[140:141], off
	global_load_dword v171, v[138:139], off
	global_load_dword v172, v[142:143], off
	v_lshlrev_b64 v[138:139], 13, v[180:181]
	v_or_b32_e32 v180, s29, v30
	v_mov_b32_e32 v149, v181
	v_mov_b32_e32 v151, v181
	v_or_b32_e32 v148, s28, v3
	v_or_b32_e32 v150, s30, v3
	v_lshlrev_b64 v[144:145], 13, v[144:145]
	v_lshlrev_b64 v[146:147], 13, v[146:147]
	v_lshl_add_u64 v[136:137], v[28:29], 0, v[152:153]
	v_lshl_add_u64 v[138:139], v[28:29], 0, v[138:139]
	v_lshlrev_b64 v[140:141], 13, v[180:181]
	v_or_b32_e32 v180, s31, v30
	v_lshlrev_b64 v[148:149], 13, v[148:149]
	v_lshlrev_b64 v[150:151], 13, v[150:151]
	v_lshl_add_u64 v[144:145], v[28:29], 0, v[144:145]
	v_lshl_add_u64 v[146:147], v[28:29], 0, v[146:147]
	global_load_dword v173, v[136:137], off
	global_load_dword v174, v[144:145], off
	global_load_dword v175, v[138:139], off
	global_load_dword v176, v[146:147], off
	v_lshl_add_u64 v[136:137], v[28:29], 0, v[140:141]
	v_lshlrev_b64 v[138:139], 13, v[180:181]
	v_lshl_add_u64 v[148:149], v[28:29], 0, v[148:149]
	v_lshl_add_u64 v[150:151], v[28:29], 0, v[150:151]
	v_lshl_add_u64 v[138:139], v[28:29], 0, v[138:139]
	global_load_dword v180, v[136:137], off
	global_load_dword v177, v[148:149], off
	global_load_dword v178, v[138:139], off
	global_load_dword v179, v[150:151], off
	s_waitcnt vmcnt(31)
	ds_write_b32 v36, v25
	s_waitcnt vmcnt(30)
	ds_write_b32 v38, v27
	s_waitcnt vmcnt(29)
	ds_write_b32 v40, v35
	s_waitcnt vmcnt(28)
	ds_write_b32 v42, v68
	s_waitcnt vmcnt(27)
	ds_write_b32 v44, v69
	s_waitcnt vmcnt(26)
	ds_write_b32 v46, v70
	s_waitcnt vmcnt(25)
	ds_write_b32 v48, v71
	s_waitcnt vmcnt(24)
	ds_write_b32 v50, v72
	s_waitcnt vmcnt(23)
	ds_write_b32 v52, v73
	s_waitcnt vmcnt(22)
	ds_write_b32 v54, v74
	s_waitcnt vmcnt(21)
	ds_write_b32 v56, v75
	s_waitcnt vmcnt(20)
	ds_write_b32 v58, v76
	s_waitcnt vmcnt(19)
	ds_write_b32 v60, v4
	s_waitcnt vmcnt(18)
	ds_write_b32 v62, v77
	s_waitcnt vmcnt(17)
	ds_write_b32 v64, v78
	s_waitcnt vmcnt(16)
	ds_write_b32 v66, v79
	v_or_b32_e32 v138, s12, v1
	v_or_b32_e32 v136, s13, v2
	s_add_i32 s5, s5, 16
	s_add_i32 s4, s4, 16
	s_add_i32 s8, s8, -16
	v_mad_u64_u32 v[136:137], vcc, v136, s17, v[6:7]
	v_mad_u64_u32 v[138:139], vcc, v138, s17, v[6:7]
	v_or_b32_e32 v137, s18, v1
	v_or_b32_e32 v139, s19, v2
	v_or_b32_e32 v146, s20, v1
	v_or_b32_e32 v144, s21, v2
	v_or_b32_e32 v150, s22, v1
	v_or_b32_e32 v148, s23, v2
	v_or_b32_e32 v154, s24, v1
	v_or_b32_e32 v152, s25, v2
	v_or_b32_e32 v158, s26, v1
	v_or_b32_e32 v156, s27, v2
	v_or_b32_e32 v162, s28, v1
	v_or_b32_e32 v160, s29, v2
	v_or_b32_e32 v166, s30, v1
	v_or_b32_e32 v164, s31, v2
	s_cmp_lg_u32 s8, 0
	v_mad_u64_u32 v[140:141], vcc, v139, s17, v[6:7]
	v_mad_u64_u32 v[142:143], vcc, v137, s17, v[6:7]
	v_mad_u64_u32 v[144:145], vcc, v144, s17, v[6:7]
	v_mad_u64_u32 v[146:147], vcc, v146, s17, v[6:7]
	v_mad_u64_u32 v[148:149], vcc, v148, s17, v[6:7]
	v_mad_u64_u32 v[150:151], vcc, v150, s17, v[6:7]
	v_mad_u64_u32 v[152:153], vcc, v152, s17, v[6:7]
	v_mad_u64_u32 v[154:155], vcc, v154, s17, v[6:7]
	v_mad_u64_u32 v[156:157], vcc, v156, s17, v[6:7]
	v_mad_u64_u32 v[158:159], vcc, v158, s17, v[6:7]
	v_mad_u64_u32 v[160:161], vcc, v160, s17, v[6:7]
	v_mad_u64_u32 v[162:163], vcc, v162, s17, v[6:7]
	v_mad_u64_u32 v[164:165], vcc, v164, s17, v[6:7]
	v_mad_u64_u32 v[166:167], vcc, v166, s17, v[6:7]
	s_waitcnt vmcnt(15)
	ds_write_b32 v136, v182
	s_waitcnt vmcnt(14)
	ds_write_b32 v138, v183
	s_waitcnt vmcnt(13)
	ds_write_b32 v140, v135
	s_waitcnt vmcnt(12)
	ds_write_b32 v142, v168
	s_waitcnt vmcnt(11)
	ds_write_b32 v144, v169
	s_waitcnt vmcnt(10)
	ds_write_b32 v146, v170
	s_waitcnt vmcnt(9)
	ds_write_b32 v148, v171
	s_waitcnt vmcnt(8)
	ds_write_b32 v150, v172
	s_waitcnt vmcnt(7)
	ds_write_b32 v152, v173
	s_waitcnt vmcnt(6)
	ds_write_b32 v154, v174
	s_waitcnt vmcnt(5)
	ds_write_b32 v156, v175
	s_waitcnt vmcnt(4)
	ds_write_b32 v158, v176
	s_waitcnt vmcnt(3)
	ds_write_b32 v160, v180
	s_waitcnt vmcnt(2)
	ds_write_b32 v162, v177
	s_waitcnt vmcnt(1)
	ds_write_b32 v164, v178
	s_waitcnt vmcnt(0)
	ds_write_b32 v166, v179
	s_waitcnt lgkmcnt(0)
	ds_read2_b32 v[28:29], v31 offset0:33 offset1:41
	ds_read2_b32 v[40:41], v31 offset1:8
	ds_read2_b32 v[42:43], v31 offset0:66 offset1:74
	ds_read2_b32 v[44:45], v31 offset0:99 offset1:107
	ds_read2_b32 v[46:47], v31 offset0:132 offset1:140
	ds_read2_b32 v[48:49], v31 offset0:165 offset1:173
	ds_read2_b32 v[50:51], v31 offset0:198 offset1:206
	ds_read2_b32 v[52:53], v31 offset0:231 offset1:239
	s_lshl_b32 s8, s3, 1
	v_or_b32_e32 v3, s2, v7
	v_lshl_add_u64 v[54:55], v[18:19], 0, s[8:9]
	v_lshlrev_b32_e32 v4, 12, v3
	s_waitcnt lgkmcnt(6)
	v_cvt_pk_bf16_f32 v36, v40, v28
	s_waitcnt lgkmcnt(4)
	v_cvt_pk_bf16_f32 v37, v42, v44
	s_waitcnt lgkmcnt(2)
	v_cvt_pk_bf16_f32 v38, v46, v48
	s_waitcnt lgkmcnt(0)
	v_cvt_pk_bf16_f32 v39, v50, v52
	v_lshl_add_u64 v[56:57], v[54:55], 0, v[4:5]
	global_store_dwordx4 v[56:57], v[36:39], off
	v_or_b32_e32 v3, s2, v32
	v_lshlrev_b32_e32 v4, 12, v3
	v_cvt_pk_bf16_f32 v36, v41, v29
	v_cvt_pk_bf16_f32 v37, v43, v45
	v_cvt_pk_bf16_f32 v38, v47, v49
	v_cvt_pk_bf16_f32 v39, v51, v53
	ds_read2_b32 v[40:41], v31 offset0:49 offset1:57
	ds_read2_b32 v[42:43], v31 offset0:16 offset1:24
	ds_read2_b32 v[44:45], v31 offset0:82 offset1:90
	ds_read2_b32 v[46:47], v31 offset0:115 offset1:123
	ds_read2_b32 v[48:49], v31 offset0:148 offset1:156
	ds_read2_b32 v[50:51], v31 offset0:181 offset1:189
	ds_read2_b32 v[52:53], v31 offset0:214 offset1:222
	ds_read2_b32 v[56:57], v31 offset0:247 offset1:255
	v_or_b32_e32 v3, s2, v33
	v_lshl_add_u64 v[28:29], v[54:55], 0, v[4:5]
	v_lshlrev_b32_e32 v4, 12, v3
	v_or_b32_e32 v3, s2, v34
	global_store_dwordx4 v[28:29], v[36:39], off
	v_lshl_add_u64 v[28:29], v[54:55], 0, v[4:5]
	v_lshlrev_b32_e32 v4, 12, v3
	s_waitcnt lgkmcnt(6)
	v_cvt_pk_bf16_f32 v36, v42, v40
	s_waitcnt lgkmcnt(4)
	v_cvt_pk_bf16_f32 v37, v44, v46
	s_waitcnt lgkmcnt(2)
	v_cvt_pk_bf16_f32 v38, v48, v50
	s_waitcnt lgkmcnt(0)
	v_cvt_pk_bf16_f32 v39, v52, v56
	global_store_dwordx4 v[28:29], v[36:39], off
	v_lshl_add_u64 v[28:29], v[54:55], 0, v[4:5]
	s_nop 0
	v_cvt_pk_bf16_f32 v36, v43, v41
	v_cvt_pk_bf16_f32 v37, v45, v47
	v_cvt_pk_bf16_f32 v38, v49, v51
	v_cvt_pk_bf16_f32 v39, v53, v57
	global_store_dwordx4 v[28:29], v[36:39], off
	s_waitcnt lgkmcnt(0)

.LBB0_144:
	s_lshl_b32 s8, s2, 1
	s_lshl_b32 s13, s3, 1
	v_or_b32_e32 v38, s13, v4
	s_add_i32 s18, s8, 4
	s_add_i32 s19, s13, 4
	s_add_i32 s20, s8, 8
	s_add_i32 s21, s13, 8
	s_add_i32 s22, s8, 12
	s_add_i32 s23, s13, 12
	s_add_i32 s26, s8, 16
	s_add_i32 s27, s13, 16
	s_add_i32 s28, s8, 20
	s_add_i32 s29, s13, 20
	s_add_i32 s30, s8, 24
	s_add_i32 s31, s13, 24
	s_add_i32 s33, s8, 28
	s_add_i32 s34, s13, 28
	v_or_b32_e32 v36, s8, v3
	v_ashrrev_i32_e32 v39, 31, v38
	v_or_b32_e32 v40, s18, v3
	v_or_b32_e32 v42, s19, v4
	v_or_b32_e32 v44, s20, v3
	v_or_b32_e32 v46, s21, v4
	v_or_b32_e32 v48, s22, v3
	v_or_b32_e32 v50, s23, v4
	v_or_b32_e32 v52, s26, v3
	v_or_b32_e32 v54, s27, v4
	v_or_b32_e32 v56, s28, v3
	v_or_b32_e32 v58, s29, v4
	v_or_b32_e32 v60, s30, v3
	v_or_b32_e32 v62, s31, v4
	v_or_b32_e32 v64, s33, v3
	v_or_b32_e32 v66, s34, v4
	v_ashrrev_i32_e32 v37, 31, v36
	v_lshlrev_b64 v[38:39], 15, v[38:39]
	v_ashrrev_i32_e32 v43, 31, v42
	v_ashrrev_i32_e32 v41, 31, v40
	v_ashrrev_i32_e32 v47, 31, v46
	v_ashrrev_i32_e32 v45, 31, v44
	v_ashrrev_i32_e32 v51, 31, v50
	v_ashrrev_i32_e32 v49, 31, v48
	v_ashrrev_i32_e32 v55, 31, v54
	v_ashrrev_i32_e32 v53, 31, v52
	v_ashrrev_i32_e32 v59, 31, v58
	v_ashrrev_i32_e32 v57, 31, v56
	v_ashrrev_i32_e32 v63, 31, v62
	v_ashrrev_i32_e32 v61, 31, v60
	v_ashrrev_i32_e32 v67, 31, v66
	v_ashrrev_i32_e32 v65, 31, v64
	v_lshlrev_b64 v[36:37], 15, v[36:37]
	v_lshl_add_u64 v[38:39], v[28:29], 0, v[38:39]
	v_lshlrev_b64 v[40:41], 15, v[40:41]
	v_lshlrev_b64 v[42:43], 15, v[42:43]
	v_lshlrev_b64 v[44:45], 15, v[44:45]
	v_lshlrev_b64 v[46:47], 15, v[46:47]
	v_lshlrev_b64 v[48:49], 15, v[48:49]
	v_lshlrev_b64 v[50:51], 15, v[50:51]
	v_lshlrev_b64 v[52:53], 15, v[52:53]
	v_lshlrev_b64 v[54:55], 15, v[54:55]
	v_lshlrev_b64 v[56:57], 15, v[56:57]
	v_lshlrev_b64 v[58:59], 15, v[58:59]
	v_lshlrev_b64 v[60:61], 15, v[60:61]
	v_lshlrev_b64 v[62:63], 15, v[62:63]
	v_lshlrev_b64 v[64:65], 15, v[64:65]
	v_lshlrev_b64 v[66:67], 15, v[66:67]
	v_lshl_add_u64 v[36:37], v[28:29], 0, v[36:37]
	v_lshl_add_u64 v[42:43], v[28:29], 0, v[42:43]
	v_lshl_add_u64 v[40:41], v[28:29], 0, v[40:41]
	v_lshl_add_u64 v[46:47], v[28:29], 0, v[46:47]
	v_lshl_add_u64 v[44:45], v[28:29], 0, v[44:45]
	v_lshl_add_u64 v[50:51], v[28:29], 0, v[50:51]
	v_lshl_add_u64 v[48:49], v[28:29], 0, v[48:49]
	v_lshl_add_u64 v[54:55], v[28:29], 0, v[54:55]
	v_lshl_add_u64 v[52:53], v[28:29], 0, v[52:53]
	v_lshl_add_u64 v[58:59], v[28:29], 0, v[58:59]
	v_lshl_add_u64 v[56:57], v[28:29], 0, v[56:57]
	v_lshl_add_u64 v[62:63], v[28:29], 0, v[62:63]
	v_lshl_add_u64 v[60:61], v[28:29], 0, v[60:61]
	v_lshl_add_u64 v[66:67], v[28:29], 0, v[66:67]
	v_lshl_add_u64 v[64:65], v[28:29], 0, v[64:65]
	global_load_dword v25, v[38:39], off
	global_load_dword v27, v[36:37], off
	global_load_dword v30, v[42:43], off
	global_load_dword v35, v[40:41], off
	global_load_dword v68, v[46:47], off
	global_load_dword v69, v[44:45], off
	global_load_dword v70, v[50:51], off
	global_load_dword v71, v[48:49], off
	global_load_dword v72, v[54:55], off
	global_load_dword v73, v[52:53], off
	global_load_dword v74, v[58:59], off
	global_load_dword v75, v[56:57], off
	global_load_dword v76, v[62:63], off
	global_load_dword v77, v[60:61], off
	global_load_dword v78, v[66:67], off
	global_load_dword v79, v[64:65], off
	v_or_b32_e32 v38, s8, v1
	v_or_b32_e32 v36, s13, v2
	s_add_i32 s3, s3, 16
	s_add_i32 s2, s2, 16
	s_add_i32 s5, s5, -16
	v_mad_u64_u32 v[36:37], vcc, v36, s17, v[6:7]
	v_mad_u64_u32 v[38:39], vcc, v38, s17, v[6:7]
	v_or_b32_e32 v37, s18, v1
	v_or_b32_e32 v39, s19, v2
	v_or_b32_e32 v46, s20, v1
	v_or_b32_e32 v44, s21, v2
	v_or_b32_e32 v50, s22, v1
	v_or_b32_e32 v48, s23, v2
	v_or_b32_e32 v54, s26, v1
	v_or_b32_e32 v52, s27, v2
	v_or_b32_e32 v58, s28, v1
	v_or_b32_e32 v56, s29, v2
	v_or_b32_e32 v62, s30, v1
	v_or_b32_e32 v60, s31, v2
	v_or_b32_e32 v66, s33, v1
	v_or_b32_e32 v64, s34, v2
	s_cmp_lg_u32 s5, 0
	v_mad_u64_u32 v[40:41], vcc, v39, s17, v[6:7]
	v_mad_u64_u32 v[42:43], vcc, v37, s17, v[6:7]
	v_mad_u64_u32 v[44:45], vcc, v44, s17, v[6:7]
	v_mad_u64_u32 v[46:47], vcc, v46, s17, v[6:7]
	v_mad_u64_u32 v[48:49], vcc, v48, s17, v[6:7]
	v_mad_u64_u32 v[50:51], vcc, v50, s17, v[6:7]
	v_mad_u64_u32 v[52:53], vcc, v52, s17, v[6:7]
	v_mad_u64_u32 v[54:55], vcc, v54, s17, v[6:7]
	v_mad_u64_u32 v[56:57], vcc, v56, s17, v[6:7]
	v_mad_u64_u32 v[58:59], vcc, v58, s17, v[6:7]
	v_mad_u64_u32 v[60:61], vcc, v60, s17, v[6:7]
	v_mad_u64_u32 v[62:63], vcc, v62, s17, v[6:7]
	v_mad_u64_u32 v[64:65], vcc, v64, s17, v[6:7]
	v_mad_u64_u32 v[66:67], vcc, v66, s17, v[6:7]
	s_nop 3
	s_lshl_b32 s8, s2, 1
	s_lshl_b32 s13, s3, 1
	v_or_b32_e32 v138, s13, v4
	s_add_i32 s18, s8, 4
	s_add_i32 s19, s13, 4
	s_add_i32 s20, s8, 8
	s_add_i32 s21, s13, 8
	s_add_i32 s22, s8, 12
	s_add_i32 s23, s13, 12
	s_add_i32 s26, s8, 16
	s_add_i32 s27, s13, 16
	s_add_i32 s28, s8, 20
	s_add_i32 s29, s13, 20
	s_add_i32 s30, s8, 24
	s_add_i32 s31, s13, 24
	s_add_i32 s33, s8, 28
	s_add_i32 s34, s13, 28
	v_or_b32_e32 v136, s8, v3
	v_ashrrev_i32_e32 v139, 31, v138
	v_or_b32_e32 v140, s18, v3
	v_or_b32_e32 v142, s19, v4
	v_or_b32_e32 v144, s20, v3
	v_or_b32_e32 v146, s21, v4
	v_or_b32_e32 v148, s22, v3
	v_or_b32_e32 v150, s23, v4
	v_or_b32_e32 v152, s26, v3
	v_or_b32_e32 v154, s27, v4
	v_or_b32_e32 v156, s28, v3
	v_or_b32_e32 v158, s29, v4
	v_or_b32_e32 v160, s30, v3
	v_or_b32_e32 v162, s31, v4
	v_or_b32_e32 v164, s33, v3
	v_or_b32_e32 v166, s34, v4
	v_ashrrev_i32_e32 v137, 31, v136
	v_lshlrev_b64 v[138:139], 15, v[138:139]
	v_ashrrev_i32_e32 v143, 31, v142
	v_ashrrev_i32_e32 v141, 31, v140
	v_ashrrev_i32_e32 v147, 31, v146
	v_ashrrev_i32_e32 v145, 31, v144
	v_ashrrev_i32_e32 v151, 31, v150
	v_ashrrev_i32_e32 v149, 31, v148
	v_ashrrev_i32_e32 v155, 31, v154
	v_ashrrev_i32_e32 v153, 31, v152
	v_ashrrev_i32_e32 v159, 31, v158
	v_ashrrev_i32_e32 v157, 31, v156
	v_ashrrev_i32_e32 v163, 31, v162
	v_ashrrev_i32_e32 v161, 31, v160
	v_ashrrev_i32_e32 v167, 31, v166
	v_ashrrev_i32_e32 v165, 31, v164
	v_lshlrev_b64 v[136:137], 15, v[136:137]
	v_lshl_add_u64 v[138:139], v[28:29], 0, v[138:139]
	v_lshlrev_b64 v[140:141], 15, v[140:141]
	v_lshlrev_b64 v[142:143], 15, v[142:143]
	v_lshlrev_b64 v[144:145], 15, v[144:145]
	v_lshlrev_b64 v[146:147], 15, v[146:147]
	v_lshlrev_b64 v[148:149], 15, v[148:149]
	v_lshlrev_b64 v[150:151], 15, v[150:151]
	v_lshlrev_b64 v[152:153], 15, v[152:153]
	v_lshlrev_b64 v[154:155], 15, v[154:155]
	v_lshlrev_b64 v[156:157], 15, v[156:157]
	v_lshlrev_b64 v[158:159], 15, v[158:159]
	v_lshlrev_b64 v[160:161], 15, v[160:161]
	v_lshlrev_b64 v[162:163], 15, v[162:163]
	v_lshlrev_b64 v[164:165], 15, v[164:165]
	v_lshlrev_b64 v[166:167], 15, v[166:167]
	v_lshl_add_u64 v[136:137], v[28:29], 0, v[136:137]
	v_lshl_add_u64 v[142:143], v[28:29], 0, v[142:143]
	v_lshl_add_u64 v[140:141], v[28:29], 0, v[140:141]
	v_lshl_add_u64 v[146:147], v[28:29], 0, v[146:147]
	v_lshl_add_u64 v[144:145], v[28:29], 0, v[144:145]
	v_lshl_add_u64 v[150:151], v[28:29], 0, v[150:151]
	v_lshl_add_u64 v[148:149], v[28:29], 0, v[148:149]
	v_lshl_add_u64 v[154:155], v[28:29], 0, v[154:155]
	v_lshl_add_u64 v[152:153], v[28:29], 0, v[152:153]
	v_lshl_add_u64 v[158:159], v[28:29], 0, v[158:159]
	v_lshl_add_u64 v[156:157], v[28:29], 0, v[156:157]
	v_lshl_add_u64 v[162:163], v[28:29], 0, v[162:163]
	v_lshl_add_u64 v[160:161], v[28:29], 0, v[160:161]
	v_lshl_add_u64 v[166:167], v[28:29], 0, v[166:167]
	v_lshl_add_u64 v[164:165], v[28:29], 0, v[164:165]
	global_load_dword v182, v[138:139], off
	global_load_dword v183, v[136:137], off
	global_load_dword v184, v[142:143], off
	global_load_dword v135, v[140:141], off
	global_load_dword v168, v[146:147], off
	global_load_dword v169, v[144:145], off
	global_load_dword v170, v[150:151], off
	global_load_dword v171, v[148:149], off
	global_load_dword v172, v[154:155], off
	global_load_dword v173, v[152:153], off
	global_load_dword v174, v[158:159], off
	global_load_dword v175, v[156:157], off
	global_load_dword v176, v[162:163], off
	global_load_dword v177, v[160:161], off
	global_load_dword v178, v[166:167], off
	global_load_dword v179, v[164:165], off
	s_waitcnt vmcnt(31)
	ds_write_b32 v36, v25
	s_waitcnt vmcnt(30)
	ds_write_b32 v38, v27
	s_waitcnt vmcnt(29)
	ds_write_b32 v40, v30
	s_waitcnt vmcnt(28)
	ds_write_b32 v42, v35
	s_waitcnt vmcnt(27)
	ds_write_b32 v44, v68
	s_waitcnt vmcnt(26)
	ds_write_b32 v46, v69
	s_waitcnt vmcnt(25)
	ds_write_b32 v48, v70
	s_waitcnt vmcnt(24)
	ds_write_b32 v50, v71
	s_waitcnt vmcnt(23)
	ds_write_b32 v52, v72
	s_waitcnt vmcnt(22)
	ds_write_b32 v54, v73
	s_waitcnt vmcnt(21)
	ds_write_b32 v56, v74
	s_waitcnt vmcnt(20)
	ds_write_b32 v58, v75
	s_waitcnt vmcnt(19)
	ds_write_b32 v60, v76
	s_waitcnt vmcnt(18)
	ds_write_b32 v62, v77
	s_waitcnt vmcnt(17)
	ds_write_b32 v64, v78
	s_waitcnt vmcnt(16)
	ds_write_b32 v66, v79
	v_or_b32_e32 v138, s8, v1
	v_or_b32_e32 v136, s13, v2
	s_add_i32 s3, s3, 16
	s_add_i32 s2, s2, 16
	s_add_i32 s5, s5, -16
	v_mad_u64_u32 v[136:137], vcc, v136, s17, v[6:7]
	v_mad_u64_u32 v[138:139], vcc, v138, s17, v[6:7]
	v_or_b32_e32 v137, s18, v1
	v_or_b32_e32 v139, s19, v2
	v_or_b32_e32 v146, s20, v1
	v_or_b32_e32 v144, s21, v2
	v_or_b32_e32 v150, s22, v1
	v_or_b32_e32 v148, s23, v2
	v_or_b32_e32 v154, s26, v1
	v_or_b32_e32 v152, s27, v2
	v_or_b32_e32 v158, s28, v1
	v_or_b32_e32 v156, s29, v2
	v_or_b32_e32 v162, s30, v1
	v_or_b32_e32 v160, s31, v2
	v_or_b32_e32 v166, s33, v1
	v_or_b32_e32 v164, s34, v2
	s_cmp_lg_u32 s5, 0
	v_mad_u64_u32 v[140:141], vcc, v139, s17, v[6:7]
	v_mad_u64_u32 v[142:143], vcc, v137, s17, v[6:7]
	v_mad_u64_u32 v[144:145], vcc, v144, s17, v[6:7]
	v_mad_u64_u32 v[146:147], vcc, v146, s17, v[6:7]
	v_mad_u64_u32 v[148:149], vcc, v148, s17, v[6:7]
	v_mad_u64_u32 v[150:151], vcc, v150, s17, v[6:7]
	v_mad_u64_u32 v[152:153], vcc, v152, s17, v[6:7]
	v_mad_u64_u32 v[154:155], vcc, v154, s17, v[6:7]
	v_mad_u64_u32 v[156:157], vcc, v156, s17, v[6:7]
	v_mad_u64_u32 v[158:159], vcc, v158, s17, v[6:7]
	v_mad_u64_u32 v[160:161], vcc, v160, s17, v[6:7]
	v_mad_u64_u32 v[162:163], vcc, v162, s17, v[6:7]
	v_mad_u64_u32 v[164:165], vcc, v164, s17, v[6:7]
	v_mad_u64_u32 v[166:167], vcc, v166, s17, v[6:7]
	s_waitcnt vmcnt(15)
	ds_write_b32 v136, v182
	s_waitcnt vmcnt(14)
	ds_write_b32 v138, v183
	s_waitcnt vmcnt(13)
	ds_write_b32 v140, v184
	s_waitcnt vmcnt(12)
	ds_write_b32 v142, v135
	s_waitcnt vmcnt(11)
	ds_write_b32 v144, v168
	s_waitcnt vmcnt(10)
	ds_write_b32 v146, v169
	s_waitcnt vmcnt(9)
	ds_write_b32 v148, v170
	s_waitcnt vmcnt(8)
	ds_write_b32 v150, v171
	s_waitcnt vmcnt(7)
	ds_write_b32 v152, v172
	s_waitcnt vmcnt(6)
	ds_write_b32 v154, v173
	s_waitcnt vmcnt(5)
	ds_write_b32 v156, v174
	s_waitcnt vmcnt(4)
	ds_write_b32 v158, v175
	s_waitcnt vmcnt(3)
	ds_write_b32 v160, v176
	s_waitcnt vmcnt(2)
	ds_write_b32 v162, v177
	s_waitcnt vmcnt(1)
	ds_write_b32 v164, v178
	s_waitcnt vmcnt(0)
	ds_write_b32 v166, v179
	s_waitcnt lgkmcnt(0)
	ds_read2_b32 v[28:29], v31 offset0:33 offset1:41
	ds_read2_b32 v[40:41], v31 offset1:8
	ds_read2_b32 v[42:43], v31 offset0:66 offset1:74
	ds_read2_b32 v[44:45], v31 offset0:99 offset1:107
	ds_read2_b32 v[46:47], v31 offset0:132 offset1:140
	ds_read2_b32 v[48:49], v31 offset0:165 offset1:173
	ds_read2_b32 v[50:51], v31 offset0:198 offset1:206
	ds_read2_b32 v[52:53], v31 offset0:231 offset1:239
	v_or_b32_e32 v56, s4, v7
	s_ashr_i32 s13, s12, 31
	v_ashrrev_i32_e32 v57, 31, v56
	v_lshl_add_u64 v[54:55], s[12:13], 1, v[22:23]
	v_lshlrev_b64 v[56:57], 12, v[56:57]
	s_waitcnt lgkmcnt(6)
	v_cvt_pk_bf16_f32 v36, v40, v28
	s_waitcnt lgkmcnt(4)
	v_cvt_pk_bf16_f32 v37, v42, v44
	s_waitcnt lgkmcnt(2)
	v_cvt_pk_bf16_f32 v38, v46, v48
	s_waitcnt lgkmcnt(0)
	v_cvt_pk_bf16_f32 v39, v50, v52
	v_lshl_add_u64 v[56:57], v[54:55], 0, v[56:57]
	v_or_b32_e32 v28, s4, v32
	global_store_dwordx4 v[56:57], v[36:39], off
	s_nop 1
	v_cvt_pk_bf16_f32 v36, v41, v29
	v_ashrrev_i32_e32 v29, 31, v28
	v_cvt_pk_bf16_f32 v37, v43, v45
	v_cvt_pk_bf16_f32 v38, v47, v49
	v_cvt_pk_bf16_f32 v39, v51, v53
	v_lshlrev_b64 v[28:29], 12, v[28:29]
	ds_read2_b32 v[40:41], v31 offset0:49 offset1:57
	ds_read2_b32 v[42:43], v31 offset0:16 offset1:24
	ds_read2_b32 v[44:45], v31 offset0:82 offset1:90
	ds_read2_b32 v[46:47], v31 offset0:115 offset1:123
	ds_read2_b32 v[48:49], v31 offset0:148 offset1:156
	ds_read2_b32 v[50:51], v31 offset0:181 offset1:189
	ds_read2_b32 v[52:53], v31 offset0:214 offset1:222
	ds_read2_b32 v[56:57], v31 offset0:247 offset1:255
	v_lshl_add_u64 v[28:29], v[54:55], 0, v[28:29]
	global_store_dwordx4 v[28:29], v[36:39], off
	v_or_b32_e32 v28, s4, v33
	v_ashrrev_i32_e32 v29, 31, v28
	v_lshlrev_b64 v[28:29], 12, v[28:29]
	s_waitcnt lgkmcnt(6)
	v_cvt_pk_bf16_f32 v36, v42, v40
	s_waitcnt lgkmcnt(4)
	v_cvt_pk_bf16_f32 v37, v44, v46
	s_waitcnt lgkmcnt(2)
	v_cvt_pk_bf16_f32 v38, v48, v50
	s_waitcnt lgkmcnt(0)
	v_cvt_pk_bf16_f32 v39, v52, v56
	v_lshl_add_u64 v[28:29], v[54:55], 0, v[28:29]
	global_store_dwordx4 v[28:29], v[36:39], off
	v_or_b32_e32 v28, s4, v34
	v_ashrrev_i32_e32 v29, 31, v28
	v_lshlrev_b64 v[28:29], 12, v[28:29]
	v_cvt_pk_bf16_f32 v36, v43, v41
	v_cvt_pk_bf16_f32 v37, v45, v47
	v_cvt_pk_bf16_f32 v38, v49, v51
	v_cvt_pk_bf16_f32 v39, v53, v57
	v_lshl_add_u64 v[28:29], v[54:55], 0, v[28:29]
	global_store_dwordx4 v[28:29], v[36:39], off
	s_waitcnt lgkmcnt(0)
	s_branch .LBB0_115
.LBB0_146:
	s_waitcnt vmcnt(0) lgkmcnt(0)
	s_barrier
	v_cmp_eq_u32_e32 vcc, 0, v212
	s_and_saveexec_b64 s[2:3], vcc
	s_cbranch_execz .Lgs0_done
	buffer_wbl2 sc1
	s_waitcnt vmcnt(0)
	s_load_dwordx2 s[4:5], s[0:1], 0xc0
	v_mov_b32_e32 v2, 0
	v_mov_b32_e32 v3, 1
	s_mov_b64 s[6:7], 0
	s_mov_b32 s8, 0
	s_waitcnt lgkmcnt(0)
	s_add_u32 s4, s4, 0x63700
	s_addc_u32 s5, s5, 0
	global_atomic_add v2, v3, s[4:5]
.Lgs0_spin:
	s_sleep 64
	global_load_dword v3, v2, s[4:5] sc1
	s_add_i32 s8, s8, 1
	s_cmp_lt_u32 s8, 0x4000
	s_cbranch_scc0 .Lgs0_out
	s_waitcnt vmcnt(0)
	v_cmp_le_u32_e32 vcc, s54, v3
	s_or_b64 s[6:7], vcc, s[6:7]
	s_andn2_b64 exec, exec, s[6:7]
	s_cbranch_execnz .Lgs0_spin
.Lgs0_out:
	s_waitcnt vmcnt(0)
	buffer_inv sc1
